# next pass's row/context DMAs issued from the previous pass's epilogue; SGU weight/V-row loads of groups 1 and 3 issued a phase earlier into registers of their own
# baseline (speedup 1.0000x reference)
.LBB0_421:
	s_ashr_i32 s6, s12, 5
	s_ashr_i32 s7, s6, 31
	s_mul_i32 s4, s6, 0x1100
	s_and_b32 s0, s10, 0xf80
	s_mul_hi_i32 s5, s6, 0x1100
	s_add_u32 s4, s4, s0
	s_addc_u32 s5, s5, 0
	v_lshl_add_u64 v[0:1], s[4:5], 0, v[98:99]
	v_lshlrev_b64 v[0:1], 10, v[0:1]
	v_lshl_add_u64 v[142:143], v[136:137], 0, v[0:1]
	global_load_dwordx4 v[0:3], v[104:105], off
	global_load_dwordx4 v[4:7], v[142:143], off offset:48
	global_load_dwordx4 v[8:11], v[142:143], off offset:32
	global_load_dwordx4 v[12:15], v[142:143], off offset:16
	global_load_dwordx4 v[16:19], v[142:143], off
	global_load_dwordx4 v[20:23], v[106:107], off
	global_load_dwordx4 v[24:27], v[108:109], off
	global_load_dwordx4 v[28:31], v[110:111], off
	v_lshl_add_u64 v[32:33], s[4:5], 0, v[100:101]
	v_lshlrev_b64 v[32:33], 10, v[32:33]
	v_lshl_add_u64 v[144:145], v[138:139], 0, v[32:33]
	v_lshl_add_u64 v[146:147], v[140:141], 0, v[32:33]
	global_load_dwordx4 v[92:95], v[144:145], off
	global_load_dwordx4 v[64:67], v[146:147], off
	global_load_dwordx4 v[88:91], v[144:145], off offset:64
	global_load_dwordx4 v[68:71], v[146:147], off offset:64
	global_load_dwordx4 v[84:87], v[144:145], off offset:128
	global_load_dwordx4 v[72:75], v[146:147], off offset:128
	global_load_dwordx4 v[80:83], v[144:145], off offset:192
	global_load_dwordx4 v[76:79], v[146:147], off offset:192
	global_load_dwordx4 v[208:211], v[112:113], off
	global_load_dwordx4 v[192:195], v[142:143], off offset:304
	global_load_dwordx4 v[196:199], v[142:143], off offset:288
	global_load_dwordx4 v[200:203], v[142:143], off offset:272
	global_load_dwordx4 v[204:207], v[142:143], off offset:256
	global_load_dwordx4 v[212:215], v[114:115], off
	global_load_dwordx4 v[218:221], v[116:117], off
	global_load_dwordx4 v[222:225], v[118:119], off
	s_waitcnt lgkmcnt(0)
	s_barrier
	v_lshl_add_u64 v[32:33], v[100:101], 0, s[0:1]
	v_lshlrev_b64 v[148:149], 11, v[32:33]
	s_lshl_b64 s[6:7], s[6:7], 23
	s_add_u32 s4, s78, s6
	s_addc_u32 s5, s79, s7
	s_add_i32 s12, s12, s3
	s_add_i32 s10, s10, s11
	s_cmpk_lt_i32 s12, 0x100
	s_waitcnt vmcnt(23)
	ds_write_b128 v160, v[0:3] offset:32768
	s_waitcnt vmcnt(18)
	ds_write_b128 v161, v[20:23] offset:32768
	s_waitcnt vmcnt(17)
	ds_write_b128 v162, v[24:27] offset:32768
	s_waitcnt vmcnt(16)
	ds_write_b128 v163, v[28:31] offset:32768
	v_lshlrev_b32_e32 v20, 16, v16
	v_and_b32_e32 v16, 0xffff0000, v16
	v_lshlrev_b32_e32 v21, 16, v17
	v_and_b32_e32 v17, 0xffff0000, v17
	v_mul_f32_e32 v0, v16, v16
	v_mul_f32_e32 v1, v17, v17
	v_fmac_f32_e32 v0, v20, v20
	v_fmac_f32_e32 v1, v21, v21
	v_lshlrev_b32_e32 v22, 16, v18
	v_and_b32_e32 v18, 0xffff0000, v18
	v_add_f32_e32 v0, v0, v1
	v_mul_f32_e32 v1, v18, v18
	v_fmac_f32_e32 v1, v22, v22
	v_lshlrev_b32_e32 v23, 16, v19
	v_and_b32_e32 v19, 0xffff0000, v19
	v_add_f32_e32 v0, v1, v0
	v_mul_f32_e32 v1, v19, v19
	v_fmac_f32_e32 v1, v23, v23
	v_and_b32_e32 v25, 0xffff0000, v12
	v_add_f32_e32 v0, v1, v0
	v_lshlrev_b32_e32 v24, 16, v12
	v_mul_f32_e32 v1, v25, v25
	v_fmac_f32_e32 v1, v24, v24
	v_and_b32_e32 v27, 0xffff0000, v13
	v_add_f32_e32 v0, v1, v0
	v_lshlrev_b32_e32 v26, 16, v13
	v_mul_f32_e32 v1, v27, v27
	v_fmac_f32_e32 v1, v26, v26
	v_and_b32_e32 v29, 0xffff0000, v14
	v_add_f32_e32 v0, v1, v0
	v_lshlrev_b32_e32 v28, 16, v14
	v_mul_f32_e32 v1, v29, v29
	v_fmac_f32_e32 v1, v28, v28
	v_and_b32_e32 v31, 0xffff0000, v15
	v_add_f32_e32 v0, v1, v0
	v_lshlrev_b32_e32 v30, 16, v15
	v_mul_f32_e32 v1, v31, v31
	v_fmac_f32_e32 v1, v30, v30
	v_and_b32_e32 v33, 0xffff0000, v8
	v_add_f32_e32 v0, v1, v0
	v_lshlrev_b32_e32 v32, 16, v8
	v_mul_f32_e32 v1, v33, v33
	v_fmac_f32_e32 v1, v32, v32
	v_and_b32_e32 v35, 0xffff0000, v9
	v_add_f32_e32 v0, v1, v0
	v_lshlrev_b32_e32 v34, 16, v9
	v_mul_f32_e32 v1, v35, v35
	v_fmac_f32_e32 v1, v34, v34
	v_and_b32_e32 v37, 0xffff0000, v10
	v_add_f32_e32 v0, v1, v0
	v_lshlrev_b32_e32 v36, 16, v10
	v_mul_f32_e32 v1, v37, v37
	v_fmac_f32_e32 v1, v36, v36
	v_and_b32_e32 v39, 0xffff0000, v11
	v_add_f32_e32 v0, v1, v0
	v_lshlrev_b32_e32 v38, 16, v11
	v_mul_f32_e32 v1, v39, v39
	v_fmac_f32_e32 v1, v38, v38
	v_and_b32_e32 v11, 0xffff0000, v5
	v_and_b32_e32 v10, 0xffff0000, v4
	v_add_f32_e32 v2, v1, v0
	v_lshlrev_b32_e32 v9, 16, v5
	v_lshlrev_b32_e32 v8, 16, v4
	v_pk_mul_f32 v[0:1], v[10:11], v[10:11]
	v_and_b32_e32 v15, 0xffff0000, v7
	v_pk_fma_f32 v[0:1], v[8:9], v[8:9], v[0:1]
	v_and_b32_e32 v14, 0xffff0000, v6
	v_add_f32_e32 v0, v0, v2
	v_add_f32_e32 v2, v1, v0
	v_lshlrev_b32_e32 v13, 16, v7
	v_lshlrev_b32_e32 v12, 16, v6
	v_pk_mul_f32 v[0:1], v[14:15], v[14:15]
	s_nop 0
	v_pk_fma_f32 v[0:1], v[12:13], v[12:13], v[0:1]
	s_nop 0
	v_add_f32_e32 v0, v0, v2
	v_add_f32_e32 v0, v1, v0
	ds_bpermute_b32 v1, v155, v0
	s_waitcnt lgkmcnt(0)
	v_add_f32_e32 v0, v0, v1
	ds_bpermute_b32 v1, v156, v0
	s_waitcnt lgkmcnt(0)
	v_add_f32_e32 v0, v0, v1
	v_fmamk_f32 v0, v0, 0x3c000000, v164
	v_rsq_f32_e32 v40, v0
	ds_read_b128 v[0:3], v157
	ds_read_b128 v[4:7], v157 offset:16
	v_mul_f32_e32 v20, v40, v20
	v_mul_f32_e32 v16, v40, v16
	s_waitcnt lgkmcnt(1)
	v_mul_f32_e32 v0, v0, v20
	v_mul_f32_e32 v1, v1, v16
	v_cvt_pk_bf16_f32 v0, v0, v1
	v_mul_f32_e32 v1, v40, v21
	v_mul_f32_e32 v1, v2, v1
	v_mul_f32_e32 v2, v40, v17
	v_mul_f32_e32 v2, v3, v2
	v_cvt_pk_bf16_f32 v1, v1, v2
	v_mul_f32_e32 v2, v40, v22
	v_mul_f32_e32 v3, v40, v18
	s_waitcnt lgkmcnt(0)
	v_mul_f32_e32 v2, v4, v2
	v_mul_f32_e32 v3, v5, v3
	v_cvt_pk_bf16_f32 v2, v2, v3
	v_mul_f32_e32 v3, v40, v23
	v_mul_f32_e32 v3, v6, v3
	v_mul_f32_e32 v4, v40, v19
	v_mul_f32_e32 v4, v7, v4
	v_cvt_pk_bf16_f32 v3, v3, v4
	ds_write_b128 v165, v[0:3]
	ds_read_b128 v[0:3], v157 offset:32
	ds_read_b128 v[4:7], v157 offset:48
	v_mul_f32_e32 v16, v40, v24
	v_mul_f32_e32 v8, v40, v8
	s_waitcnt lgkmcnt(1)
	v_mul_f32_e32 v0, v16, v0
	v_mul_f32_e32 v16, v40, v25
	v_mul_f32_e32 v1, v16, v1
	v_cvt_pk_bf16_f32 v0, v0, v1
	v_mul_f32_e32 v1, v40, v26
	v_mul_f32_e32 v1, v1, v2
	v_mul_f32_e32 v2, v40, v27
	v_mul_f32_e32 v2, v2, v3
	v_cvt_pk_bf16_f32 v1, v1, v2
	v_mul_f32_e32 v2, v40, v28
	v_mul_f32_e32 v3, v40, v29
	s_waitcnt lgkmcnt(0)
	v_mul_f32_e32 v2, v2, v4
	v_mul_f32_e32 v3, v3, v5
	v_cvt_pk_bf16_f32 v2, v2, v3
	v_mul_f32_e32 v3, v40, v30
	v_mul_f32_e32 v3, v3, v6
	v_mul_f32_e32 v4, v40, v31
	v_mul_f32_e32 v4, v4, v7
	v_cvt_pk_bf16_f32 v3, v3, v4
	ds_write_b128 v165, v[0:3] offset:16
	ds_read_b128 v[0:3], v157 offset:64
	ds_read_b128 v[4:7], v157 offset:80
	v_mul_f32_e32 v16, v40, v32
	s_waitcnt lgkmcnt(1)
	v_mul_f32_e32 v0, v16, v0
	v_mul_f32_e32 v16, v40, v33
	v_mul_f32_e32 v1, v16, v1
	v_cvt_pk_bf16_f32 v0, v0, v1
	v_mul_f32_e32 v1, v40, v34
	v_mul_f32_e32 v1, v1, v2
	v_mul_f32_e32 v2, v40, v35
	v_mul_f32_e32 v2, v2, v3
	v_cvt_pk_bf16_f32 v1, v1, v2
	v_mul_f32_e32 v2, v40, v36
	v_mul_f32_e32 v3, v40, v37
	s_waitcnt lgkmcnt(0)
	v_mul_f32_e32 v2, v2, v4
	v_mul_f32_e32 v3, v3, v5
	v_cvt_pk_bf16_f32 v2, v2, v3
	v_mul_f32_e32 v3, v40, v38
	v_mul_f32_e32 v3, v3, v6
	v_mul_f32_e32 v4, v40, v39
	v_mul_f32_e32 v4, v4, v7
	v_cvt_pk_bf16_f32 v3, v3, v4
	ds_write_b128 v165, v[0:3] offset:32
	ds_read_b128 v[0:3], v157 offset:96
	ds_read_b128 v[4:7], v157 offset:112
	s_waitcnt lgkmcnt(1)
	v_mul_f32_e32 v0, v8, v0
	v_mul_f32_e32 v8, v40, v10
	v_mul_f32_e32 v1, v8, v1
	v_cvt_pk_bf16_f32 v0, v0, v1
	v_mul_f32_e32 v1, v40, v9
	v_mul_f32_e32 v1, v1, v2
	v_mul_f32_e32 v2, v40, v11
	v_mul_f32_e32 v2, v2, v3
	v_cvt_pk_bf16_f32 v1, v1, v2
	v_mul_f32_e32 v2, v40, v12
	v_mul_f32_e32 v3, v40, v14
	s_waitcnt lgkmcnt(0)
	v_mul_f32_e32 v2, v2, v4
	v_mul_f32_e32 v3, v3, v5
	v_cvt_pk_bf16_f32 v2, v2, v3
	v_mul_f32_e32 v3, v40, v13
	v_mul_f32_e32 v3, v3, v6
	v_mul_f32_e32 v4, v40, v15
	v_mul_f32_e32 v4, v4, v7
	v_cvt_pk_bf16_f32 v3, v3, v4
	ds_write_b128 v165, v[0:3] offset:48
	s_waitcnt lgkmcnt(0)
	s_barrier
	global_load_dwordx4 v[28:31], v[144:145], off offset:256
	global_load_dwordx4 v[24:27], v[146:147], off offset:256
	global_load_dwordx4 v[20:23], v[144:145], off offset:320
	global_load_dwordx4 v[16:19], v[146:147], off offset:320
	global_load_dwordx4 v[12:15], v[144:145], off offset:384
	global_load_dwordx4 v[8:11], v[146:147], off offset:384
	global_load_dwordx4 v[4:7], v[144:145], off offset:448
	global_load_dwordx4 v[0:3], v[146:147], off offset:448
	ds_read_b128 v[168:171], v166 offset:32768
	ds_read_b128 v[172:175], v166 offset:32832
	ds_read_b128 v[176:179], v166 offset:32896
	ds_read_b128 v[180:183], v166 offset:32960
	ds_read_b32 v167, v158 offset:2048
	ds_read_b64_tr_b16 v[184:185], v159
	ds_read_b64_tr_b16 v[186:187], v159 offset:1088
	ds_read_b64_tr_b16 v[188:189], v159 offset:8704
	ds_read_b64_tr_b16 v[190:191], v159 offset:9792
	s_waitcnt lgkmcnt(2)
	v_mfma_f32_16x16x32_bf16 v[184:187], v[184:187], v[168:171], 0
	s_waitcnt lgkmcnt(0)
	v_mfma_f32_16x16x32_bf16 v[184:187], v[188:191], v[172:175], v[184:187]
	ds_read_b64_tr_b16 v[188:189], v159 offset:17408
	ds_read_b64_tr_b16 v[190:191], v159 offset:18496
	s_waitcnt lgkmcnt(0)
	v_mfma_f32_16x16x32_bf16 v[184:187], v[188:191], v[176:179], v[184:187]
	ds_read_b64_tr_b16 v[188:189], v159 offset:26112
	ds_read_b64_tr_b16 v[190:191], v159 offset:27200
	s_waitcnt lgkmcnt(0)
	v_mfma_f32_16x16x32_bf16 v[184:187], v[188:191], v[180:183], v[184:187]
	s_waitcnt vmcnt(23)
	v_lshlrev_b32_e32 v188, 16, v92
	v_and_b32_e32 v92, 0xffff0000, v92
	s_nop 4
	v_add_f32_e32 v184, v167, v184
	v_add_f32_e32 v185, v167, v185
	v_mul_f32_e32 v184, v184, v188
	s_waitcnt vmcnt(22)
	v_lshlrev_b32_e32 v188, 16, v64
	v_mul_f32_e32 v92, v185, v92
	v_and_b32_e32 v64, 0xffff0000, v64
	v_mul_f32_e32 v64, v92, v64
	v_lshlrev_b32_e32 v92, 16, v93
	v_add_f32_e32 v185, v167, v186
	v_mul_f32_e32 v92, v185, v92
	v_lshlrev_b32_e32 v185, 16, v65
	v_mul_f32_e32 v92, v92, v185
	v_and_b32_e32 v93, 0xffff0000, v93
	v_add_f32_e32 v185, v167, v187
	v_mul_f32_e32 v93, v185, v93
	v_and_b32_e32 v65, 0xffff0000, v65
	v_mul_f32_e32 v184, v184, v188
	v_mul_f32_e32 v65, v93, v65
	v_cvt_pk_bf16_f32 v64, v184, v64
	v_cvt_pk_bf16_f32 v65, v92, v65
	ds_read_b64_tr_b16 v[184:185], v159 offset:8
	ds_read_b64_tr_b16 v[186:187], v159 offset:1096
	ds_read_b64_tr_b16 v[188:189], v159 offset:8712
	ds_read_b64_tr_b16 v[190:191], v159 offset:9800
	s_waitcnt lgkmcnt(2)
	v_mfma_f32_16x16x32_bf16 v[184:187], v[184:187], v[168:171], 0
	v_lshlrev_b32_e32 v92, 16, v94
	s_waitcnt lgkmcnt(0)
	v_mfma_f32_16x16x32_bf16 v[184:187], v[188:191], v[172:175], v[184:187]
	ds_read_b64_tr_b16 v[188:189], v159 offset:17416
	ds_read_b64_tr_b16 v[190:191], v159 offset:18504
	s_waitcnt lgkmcnt(0)
	v_mfma_f32_16x16x32_bf16 v[184:187], v[188:191], v[176:179], v[184:187]
	ds_read_b64_tr_b16 v[188:189], v159 offset:26120
	ds_read_b64_tr_b16 v[190:191], v159 offset:27208
	s_waitcnt lgkmcnt(0)
	v_mfma_f32_16x16x32_bf16 v[184:187], v[188:191], v[180:183], v[184:187]
	s_nop 7
	v_add_f32_e32 v93, v167, v184
	v_mul_f32_e32 v92, v93, v92
	v_lshlrev_b32_e32 v93, 16, v66
	v_mul_f32_e32 v92, v92, v93
	v_and_b32_e32 v93, 0xffff0000, v94
	v_add_f32_e32 v94, v167, v185
	v_mul_f32_e32 v93, v94, v93
	v_and_b32_e32 v66, 0xffff0000, v66
	v_mul_f32_e32 v66, v93, v66
	v_lshlrev_b32_e32 v93, 16, v95
	v_add_f32_e32 v94, v167, v186
	v_mul_f32_e32 v93, v94, v93
	v_lshlrev_b32_e32 v94, 16, v67
	v_mul_f32_e32 v93, v93, v94
	v_and_b32_e32 v94, 0xffff0000, v95
	v_add_f32_e32 v95, v167, v187
	v_mul_f32_e32 v94, v95, v94
	v_and_b32_e32 v67, 0xffff0000, v67
	v_mul_f32_e32 v67, v94, v67
	v_cvt_pk_bf16_f32 v66, v92, v66
	v_cvt_pk_bf16_f32 v67, v93, v67
	ds_read_b64_tr_b16 v[92:93], v159 offset:64
	ds_read_b64_tr_b16 v[94:95], v159 offset:1152
	ds_read_b64_tr_b16 v[184:185], v159 offset:8768
	ds_read_b64_tr_b16 v[186:187], v159 offset:9856
	s_waitcnt lgkmcnt(2)
	v_mfma_f32_16x16x32_bf16 v[92:95], v[92:95], v[168:171], 0
	s_waitcnt lgkmcnt(0)
	v_mfma_f32_16x16x32_bf16 v[92:95], v[184:187], v[172:175], v[92:95]
	ds_read_b64_tr_b16 v[184:185], v159 offset:17472
	ds_read_b64_tr_b16 v[186:187], v159 offset:18560
	s_waitcnt lgkmcnt(0)
	v_mfma_f32_16x16x32_bf16 v[92:95], v[184:187], v[176:179], v[92:95]
	ds_read_b64_tr_b16 v[184:185], v159 offset:26176
	ds_read_b64_tr_b16 v[186:187], v159 offset:27264
	s_waitcnt lgkmcnt(0)
	v_mfma_f32_16x16x32_bf16 v[92:95], v[184:187], v[180:183], v[92:95]
	s_waitcnt vmcnt(21)
	v_lshlrev_b32_e32 v184, 16, v88
	v_and_b32_e32 v88, 0xffff0000, v88
	s_nop 4
	v_add_f32_e32 v92, v167, v92
	v_add_f32_e32 v93, v167, v93
	v_mul_f32_e32 v92, v92, v184
	s_waitcnt vmcnt(20)
	v_lshlrev_b32_e32 v184, 16, v68
	v_mul_f32_e32 v88, v93, v88
	v_and_b32_e32 v68, 0xffff0000, v68
	v_mul_f32_e32 v68, v88, v68
	v_lshlrev_b32_e32 v88, 16, v89
	v_add_f32_e32 v93, v167, v94
	v_mul_f32_e32 v88, v93, v88
	v_lshlrev_b32_e32 v93, 16, v69
	v_mul_f32_e32 v88, v88, v93
	v_and_b32_e32 v89, 0xffff0000, v89
	v_add_f32_e32 v93, v167, v95
	v_mul_f32_e32 v89, v93, v89
	v_and_b32_e32 v69, 0xffff0000, v69
	v_mul_f32_e32 v92, v92, v184
	v_mul_f32_e32 v69, v89, v69
	v_cvt_pk_bf16_f32 v68, v92, v68
	v_cvt_pk_bf16_f32 v69, v88, v69
	ds_read_b64_tr_b16 v[92:93], v159 offset:72
	ds_read_b64_tr_b16 v[94:95], v159 offset:1160
	ds_read_b64_tr_b16 v[184:185], v159 offset:8776
	ds_read_b64_tr_b16 v[186:187], v159 offset:9864
	s_waitcnt lgkmcnt(2)
	v_mfma_f32_16x16x32_bf16 v[92:95], v[92:95], v[168:171], 0
	v_lshlrev_b32_e32 v88, 16, v90
	s_waitcnt lgkmcnt(0)
	v_mfma_f32_16x16x32_bf16 v[92:95], v[184:187], v[172:175], v[92:95]
	ds_read_b64_tr_b16 v[184:185], v159 offset:17480
	ds_read_b64_tr_b16 v[186:187], v159 offset:18568
	s_waitcnt lgkmcnt(0)
	v_mfma_f32_16x16x32_bf16 v[92:95], v[184:187], v[176:179], v[92:95]
	ds_read_b64_tr_b16 v[184:185], v159 offset:26184
	ds_read_b64_tr_b16 v[186:187], v159 offset:27272
	s_waitcnt lgkmcnt(0)
	v_mfma_f32_16x16x32_bf16 v[92:95], v[184:187], v[180:183], v[92:95]
	s_nop 7
	v_add_f32_e32 v89, v167, v92
	v_mul_f32_e32 v88, v89, v88
	v_lshlrev_b32_e32 v89, 16, v70
	v_mul_f32_e32 v88, v88, v89
	v_and_b32_e32 v89, 0xffff0000, v90
	v_add_f32_e32 v90, v167, v93
	v_mul_f32_e32 v89, v90, v89
	v_and_b32_e32 v70, 0xffff0000, v70
	v_mul_f32_e32 v70, v89, v70
	v_lshlrev_b32_e32 v89, 16, v91
	v_add_f32_e32 v90, v167, v94
	v_mul_f32_e32 v89, v90, v89
	v_lshlrev_b32_e32 v90, 16, v71
	v_mul_f32_e32 v89, v89, v90
	v_and_b32_e32 v90, 0xffff0000, v91
	v_add_f32_e32 v91, v167, v95
	v_mul_f32_e32 v90, v91, v90
	v_and_b32_e32 v71, 0xffff0000, v71
	v_mul_f32_e32 v71, v90, v71
	v_cvt_pk_bf16_f32 v70, v88, v70
	v_cvt_pk_bf16_f32 v71, v89, v71
	ds_read_b64_tr_b16 v[88:89], v159 offset:128
	ds_read_b64_tr_b16 v[90:91], v159 offset:1216
	ds_read_b64_tr_b16 v[92:93], v159 offset:8832
	ds_read_b64_tr_b16 v[94:95], v159 offset:9920
	s_waitcnt lgkmcnt(2)
	v_mfma_f32_16x16x32_bf16 v[88:91], v[88:91], v[168:171], 0
	s_waitcnt lgkmcnt(0)
	v_mfma_f32_16x16x32_bf16 v[88:91], v[92:95], v[172:175], v[88:91]
	ds_read_b64_tr_b16 v[92:93], v159 offset:17536
	ds_read_b64_tr_b16 v[94:95], v159 offset:18624
	s_waitcnt lgkmcnt(0)
	v_mfma_f32_16x16x32_bf16 v[88:91], v[92:95], v[176:179], v[88:91]
	ds_read_b64_tr_b16 v[92:93], v159 offset:26240
	ds_read_b64_tr_b16 v[94:95], v159 offset:27328
	s_waitcnt lgkmcnt(0)
	v_mfma_f32_16x16x32_bf16 v[88:91], v[92:95], v[180:183], v[88:91]
	s_waitcnt vmcnt(19)
	v_lshlrev_b32_e32 v92, 16, v84
	v_and_b32_e32 v84, 0xffff0000, v84
	s_nop 4
	v_add_f32_e32 v88, v167, v88
	v_add_f32_e32 v89, v167, v89
	v_mul_f32_e32 v88, v88, v92
	s_waitcnt vmcnt(18)
	v_lshlrev_b32_e32 v92, 16, v72
	v_mul_f32_e32 v84, v89, v84
	v_and_b32_e32 v72, 0xffff0000, v72
	v_mul_f32_e32 v72, v84, v72
	v_lshlrev_b32_e32 v84, 16, v85
	v_add_f32_e32 v89, v167, v90
	v_mul_f32_e32 v84, v89, v84
	v_lshlrev_b32_e32 v89, 16, v73
	v_mul_f32_e32 v84, v84, v89
	v_and_b32_e32 v85, 0xffff0000, v85
	v_add_f32_e32 v89, v167, v91
	v_mul_f32_e32 v85, v89, v85
	v_and_b32_e32 v73, 0xffff0000, v73
	v_mul_f32_e32 v88, v88, v92
	v_mul_f32_e32 v73, v85, v73
	v_cvt_pk_bf16_f32 v72, v88, v72
	v_cvt_pk_bf16_f32 v73, v84, v73
	ds_read_b64_tr_b16 v[88:89], v159 offset:136
	ds_read_b64_tr_b16 v[90:91], v159 offset:1224
	ds_read_b64_tr_b16 v[92:93], v159 offset:8840
	ds_read_b64_tr_b16 v[94:95], v159 offset:9928
	s_waitcnt lgkmcnt(2)
	v_mfma_f32_16x16x32_bf16 v[88:91], v[88:91], v[168:171], 0
	v_lshlrev_b32_e32 v84, 16, v86
	s_waitcnt lgkmcnt(0)
	v_mfma_f32_16x16x32_bf16 v[88:91], v[92:95], v[172:175], v[88:91]
	ds_read_b64_tr_b16 v[92:93], v159 offset:17544
	ds_read_b64_tr_b16 v[94:95], v159 offset:18632
	s_waitcnt lgkmcnt(0)
	v_mfma_f32_16x16x32_bf16 v[88:91], v[92:95], v[176:179], v[88:91]
	ds_read_b64_tr_b16 v[92:93], v159 offset:26248
	ds_read_b64_tr_b16 v[94:95], v159 offset:27336
	s_waitcnt lgkmcnt(0)
	v_mfma_f32_16x16x32_bf16 v[88:91], v[92:95], v[180:183], v[88:91]
	s_nop 7
	v_add_f32_e32 v85, v167, v88
	v_mul_f32_e32 v84, v85, v84
	v_lshlrev_b32_e32 v85, 16, v74
	v_mul_f32_e32 v84, v84, v85
	v_and_b32_e32 v85, 0xffff0000, v86
	v_add_f32_e32 v86, v167, v89
	v_mul_f32_e32 v85, v86, v85
	v_and_b32_e32 v74, 0xffff0000, v74
	v_mul_f32_e32 v74, v85, v74
	v_lshlrev_b32_e32 v85, 16, v87
	v_add_f32_e32 v86, v167, v90
	v_mul_f32_e32 v85, v86, v85
	v_lshlrev_b32_e32 v86, 16, v75
	v_mul_f32_e32 v85, v85, v86
	v_and_b32_e32 v86, 0xffff0000, v87
	v_add_f32_e32 v87, v167, v91
	v_mul_f32_e32 v86, v87, v86
	v_and_b32_e32 v75, 0xffff0000, v75
	v_mul_f32_e32 v75, v86, v75
	v_cvt_pk_bf16_f32 v74, v84, v74
	v_cvt_pk_bf16_f32 v75, v85, v75
	ds_read_b64_tr_b16 v[84:85], v159 offset:192
	ds_read_b64_tr_b16 v[86:87], v159 offset:1280
	ds_read_b64_tr_b16 v[88:89], v159 offset:8896
	ds_read_b64_tr_b16 v[90:91], v159 offset:9984
	s_waitcnt lgkmcnt(2)
	v_mfma_f32_16x16x32_bf16 v[84:87], v[84:87], v[168:171], 0
	s_waitcnt lgkmcnt(0)
	v_mfma_f32_16x16x32_bf16 v[84:87], v[88:91], v[172:175], v[84:87]
	ds_read_b64_tr_b16 v[88:89], v159 offset:17600
	ds_read_b64_tr_b16 v[90:91], v159 offset:18688
	s_waitcnt lgkmcnt(0)
	v_mfma_f32_16x16x32_bf16 v[84:87], v[88:91], v[176:179], v[84:87]
	ds_read_b64_tr_b16 v[88:89], v159 offset:26304
	ds_read_b64_tr_b16 v[90:91], v159 offset:27392
	s_waitcnt lgkmcnt(0)
	v_mfma_f32_16x16x32_bf16 v[84:87], v[88:91], v[180:183], v[84:87]
	s_waitcnt vmcnt(17)
	v_lshlrev_b32_e32 v88, 16, v80
	v_and_b32_e32 v80, 0xffff0000, v80
	s_nop 4
	v_add_f32_e32 v84, v167, v84
	v_add_f32_e32 v85, v167, v85
	v_mul_f32_e32 v84, v84, v88
	s_waitcnt vmcnt(16)
	v_lshlrev_b32_e32 v88, 16, v76
	v_mul_f32_e32 v80, v85, v80
	v_and_b32_e32 v76, 0xffff0000, v76
	v_mul_f32_e32 v76, v80, v76
	v_lshlrev_b32_e32 v80, 16, v81
	v_add_f32_e32 v85, v167, v86
	v_mul_f32_e32 v80, v85, v80
	v_lshlrev_b32_e32 v85, 16, v77
	v_mul_f32_e32 v80, v80, v85
	v_and_b32_e32 v81, 0xffff0000, v81
	v_add_f32_e32 v85, v167, v87
	v_mul_f32_e32 v81, v85, v81
	v_and_b32_e32 v77, 0xffff0000, v77
	v_mul_f32_e32 v84, v84, v88
	v_mul_f32_e32 v77, v81, v77
	v_cvt_pk_bf16_f32 v76, v84, v76
	v_cvt_pk_bf16_f32 v77, v80, v77
	ds_read_b64_tr_b16 v[84:85], v159 offset:200
	ds_read_b64_tr_b16 v[86:87], v159 offset:1288
	ds_read_b64_tr_b16 v[88:89], v159 offset:8904
	ds_read_b64_tr_b16 v[90:91], v159 offset:9992
	s_waitcnt lgkmcnt(2)
	v_mfma_f32_16x16x32_bf16 v[84:87], v[84:87], v[168:171], 0
	v_lshlrev_b32_e32 v80, 16, v82
	s_waitcnt lgkmcnt(0)
	v_mfma_f32_16x16x32_bf16 v[84:87], v[88:91], v[172:175], v[84:87]
	ds_read_b64_tr_b16 v[88:89], v159 offset:17608
	ds_read_b64_tr_b16 v[90:91], v159 offset:18696
	s_waitcnt lgkmcnt(0)
	v_mfma_f32_16x16x32_bf16 v[84:87], v[88:91], v[176:179], v[84:87]
	ds_read_b64_tr_b16 v[88:89], v159 offset:26312
	ds_read_b64_tr_b16 v[90:91], v159 offset:27400
	s_waitcnt lgkmcnt(0)
	v_mfma_f32_16x16x32_bf16 v[84:87], v[88:91], v[180:183], v[84:87]
	s_nop 7
	v_add_f32_e32 v81, v167, v84
	v_mul_f32_e32 v80, v81, v80
	v_lshlrev_b32_e32 v81, 16, v78
	v_mul_f32_e32 v80, v80, v81
	v_and_b32_e32 v81, 0xffff0000, v82
	v_add_f32_e32 v82, v167, v85
	v_mul_f32_e32 v81, v82, v81
	v_and_b32_e32 v78, 0xffff0000, v78
	v_mul_f32_e32 v78, v81, v78
	v_lshlrev_b32_e32 v81, 16, v83
	v_add_f32_e32 v82, v167, v86
	v_mul_f32_e32 v81, v82, v81
	v_lshlrev_b32_e32 v82, 16, v79
	v_mul_f32_e32 v81, v81, v82
	v_and_b32_e32 v82, 0xffff0000, v83
	v_add_f32_e32 v83, v167, v87
	v_mul_f32_e32 v82, v83, v82
	v_and_b32_e32 v79, 0xffff0000, v79
	v_mul_f32_e32 v79, v82, v79
	v_cvt_pk_bf16_f32 v78, v80, v78
	v_cvt_pk_bf16_f32 v79, v81, v79
	v_lshl_add_u64 v[80:81], s[4:5], 0, v[148:149]
	v_lshl_add_u64 v[148:149], v[80:81], 0, v[102:103]
	global_store_dwordx4 v[148:149], v[64:67], off
	global_store_dwordx4 v[148:149], v[68:71], off offset:64
	global_store_dwordx4 v[148:149], v[72:75], off offset:128
	global_store_dwordx4 v[148:149], v[76:79], off offset:192
	s_barrier
	s_waitcnt vmcnt(19)
	ds_write_b128 v160, v[208:211] offset:32768
	s_waitcnt vmcnt(14)
	ds_write_b128 v161, v[212:215] offset:32768
	s_waitcnt vmcnt(13)
	ds_write_b128 v162, v[218:221] offset:32768
	s_waitcnt vmcnt(12)
	ds_write_b128 v163, v[222:225] offset:32768
	v_and_b32_e32 v209, 0xffff0000, v204
	v_and_b32_e32 v211, 0xffff0000, v205
	v_lshlrev_b32_e32 v208, 16, v204
	v_mul_f32_e32 v204, v209, v209
	v_lshlrev_b32_e32 v210, 16, v205
	v_mul_f32_e32 v205, v211, v211
	v_fmac_f32_e32 v204, v208, v208
	v_fmac_f32_e32 v205, v210, v210
	v_and_b32_e32 v213, 0xffff0000, v206
	v_add_f32_e32 v204, v204, v205
	v_lshlrev_b32_e32 v212, 16, v206
	v_mul_f32_e32 v205, v213, v213
	v_fmac_f32_e32 v205, v212, v212
	v_and_b32_e32 v215, 0xffff0000, v207
	v_add_f32_e32 v204, v205, v204
	v_lshlrev_b32_e32 v214, 16, v207
	v_mul_f32_e32 v205, v215, v215
	v_and_b32_e32 v219, 0xffff0000, v200
	v_fmac_f32_e32 v205, v214, v214
	v_lshlrev_b32_e32 v218, 16, v200
	v_mul_f32_e32 v200, v219, v219
	v_and_b32_e32 v221, 0xffff0000, v201
	v_add_f32_e32 v204, v205, v204
	v_fmac_f32_e32 v200, v218, v218
	v_lshlrev_b32_e32 v220, 16, v201
	v_mul_f32_e32 v201, v221, v221
	v_add_f32_e32 v200, v200, v204
	v_fmac_f32_e32 v201, v220, v220
	v_and_b32_e32 v223, 0xffff0000, v202
	v_add_f32_e32 v200, v201, v200
	v_lshlrev_b32_e32 v222, 16, v202
	v_mul_f32_e32 v201, v223, v223
	v_fmac_f32_e32 v201, v222, v222
	v_and_b32_e32 v225, 0xffff0000, v203
	v_add_f32_e32 v200, v201, v200
	v_lshlrev_b32_e32 v224, 16, v203
	v_mul_f32_e32 v201, v225, v225
	v_and_b32_e32 v65, 0xffff0000, v196
	v_fmac_f32_e32 v201, v224, v224
	v_lshlrev_b32_e32 v64, 16, v196
	v_mul_f32_e32 v196, v65, v65
	v_and_b32_e32 v67, 0xffff0000, v197
	v_add_f32_e32 v200, v201, v200
	v_fmac_f32_e32 v196, v64, v64
	v_lshlrev_b32_e32 v66, 16, v197
	v_mul_f32_e32 v197, v67, v67
	v_add_f32_e32 v196, v196, v200
	v_fmac_f32_e32 v197, v66, v66
	v_and_b32_e32 v69, 0xffff0000, v198
	v_add_f32_e32 v196, v197, v196
	v_lshlrev_b32_e32 v68, 16, v198
	v_mul_f32_e32 v197, v69, v69
	v_fmac_f32_e32 v197, v68, v68
	v_and_b32_e32 v71, 0xffff0000, v199
	v_add_f32_e32 v196, v197, v196
	v_lshlrev_b32_e32 v70, 16, v199
	v_mul_f32_e32 v197, v71, v71
	v_and_b32_e32 v203, 0xffff0000, v193
	v_and_b32_e32 v202, 0xffff0000, v192
	v_fmac_f32_e32 v197, v70, v70
	v_lshlrev_b32_e32 v201, 16, v193
	v_lshlrev_b32_e32 v200, 16, v192
	v_pk_mul_f32 v[192:193], v[202:203], v[202:203]
	v_add_f32_e32 v196, v197, v196
	v_pk_fma_f32 v[192:193], v[200:201], v[200:201], v[192:193]
	v_and_b32_e32 v207, 0xffff0000, v195
	v_add_f32_e32 v192, v192, v196
	v_and_b32_e32 v206, 0xffff0000, v194
	v_add_f32_e32 v196, v193, v192
	v_lshlrev_b32_e32 v205, 16, v195
	v_lshlrev_b32_e32 v204, 16, v194
	v_pk_mul_f32 v[192:193], v[206:207], v[206:207]
	s_nop 0
	v_pk_fma_f32 v[192:193], v[204:205], v[204:205], v[192:193]
	s_nop 0
	v_add_f32_e32 v192, v192, v196
	v_add_f32_e32 v192, v193, v192
	ds_bpermute_b32 v193, v155, v192
	s_waitcnt lgkmcnt(0)
	v_add_f32_e32 v192, v192, v193
	ds_bpermute_b32 v193, v156, v192
	s_waitcnt lgkmcnt(0)
	v_add_f32_e32 v192, v192, v193
	v_fmamk_f32 v192, v192, 0x3c000000, v164
	v_rsq_f32_e32 v72, v192
	ds_read_b128 v[192:195], v157 offset:512
	ds_read_b128 v[196:199], v157 offset:528
	v_mul_f32_e32 v208, v72, v208
	s_waitcnt lgkmcnt(1)
	v_mul_f32_e32 v192, v192, v208
	v_mul_f32_e32 v208, v72, v209
	v_mul_f32_e32 v193, v193, v208
	v_cvt_pk_bf16_f32 v192, v192, v193
	v_mul_f32_e32 v193, v72, v210
	v_mul_f32_e32 v193, v194, v193
	v_mul_f32_e32 v194, v72, v211
	v_mul_f32_e32 v194, v195, v194
	v_cvt_pk_bf16_f32 v193, v193, v194
	v_mul_f32_e32 v194, v72, v212
	v_mul_f32_e32 v195, v72, v213
	s_waitcnt lgkmcnt(0)
	v_mul_f32_e32 v194, v196, v194
	v_mul_f32_e32 v195, v197, v195
	v_cvt_pk_bf16_f32 v194, v194, v195
	v_mul_f32_e32 v195, v72, v214
	v_mul_f32_e32 v195, v198, v195
	v_mul_f32_e32 v196, v72, v215
	v_mul_f32_e32 v196, v199, v196
	v_cvt_pk_bf16_f32 v195, v195, v196
	ds_write_b128 v165, v[192:195]
	ds_read_b128 v[192:195], v157 offset:544
	ds_read_b128 v[196:199], v157 offset:560
	v_mul_f32_e32 v208, v72, v218
	v_mul_f32_e32 v200, v72, v200
	s_waitcnt lgkmcnt(1)
	v_mul_f32_e32 v192, v208, v192
	v_mul_f32_e32 v208, v72, v219
	v_mul_f32_e32 v193, v208, v193
	v_cvt_pk_bf16_f32 v192, v192, v193
	v_mul_f32_e32 v193, v72, v220
	v_mul_f32_e32 v193, v193, v194
	v_mul_f32_e32 v194, v72, v221
	v_mul_f32_e32 v194, v194, v195
	v_cvt_pk_bf16_f32 v193, v193, v194
	v_mul_f32_e32 v194, v72, v222
	v_mul_f32_e32 v195, v72, v223
	s_waitcnt lgkmcnt(0)
	v_mul_f32_e32 v194, v194, v196
	v_mul_f32_e32 v195, v195, v197
	v_cvt_pk_bf16_f32 v194, v194, v195
	v_mul_f32_e32 v195, v72, v224
	v_mul_f32_e32 v195, v195, v198
	v_mul_f32_e32 v196, v72, v225
	v_mul_f32_e32 v196, v196, v199
	v_cvt_pk_bf16_f32 v195, v195, v196
	ds_write_b128 v165, v[192:195] offset:16
	ds_read_b128 v[192:195], v157 offset:576
	ds_read_b128 v[196:199], v157 offset:592
	v_mul_f32_e32 v208, v72, v64
	s_waitcnt lgkmcnt(1)
	v_mul_f32_e32 v192, v208, v192
	v_mul_f32_e32 v208, v72, v65
	v_mul_f32_e32 v193, v208, v193
	v_cvt_pk_bf16_f32 v192, v192, v193
	v_mul_f32_e32 v193, v72, v66
	v_mul_f32_e32 v193, v193, v194
	v_mul_f32_e32 v194, v72, v67
	v_mul_f32_e32 v194, v194, v195
	v_cvt_pk_bf16_f32 v193, v193, v194
	v_mul_f32_e32 v194, v72, v68
	v_mul_f32_e32 v195, v72, v69
	s_waitcnt lgkmcnt(0)
	v_mul_f32_e32 v194, v194, v196
	v_mul_f32_e32 v195, v195, v197
	v_cvt_pk_bf16_f32 v194, v194, v195
	v_mul_f32_e32 v195, v72, v70
	v_mul_f32_e32 v195, v195, v198
	v_mul_f32_e32 v196, v72, v71
	v_mul_f32_e32 v196, v196, v199
	v_cvt_pk_bf16_f32 v195, v195, v196
	ds_write_b128 v165, v[192:195] offset:32
	ds_read_b128 v[192:195], v157 offset:608
	ds_read_b128 v[196:199], v157 offset:624
	s_waitcnt lgkmcnt(1)
	v_mul_f32_e32 v192, v200, v192
	v_mul_f32_e32 v200, v72, v202
	v_mul_f32_e32 v193, v200, v193
	v_cvt_pk_bf16_f32 v192, v192, v193
	v_mul_f32_e32 v193, v72, v201
	v_mul_f32_e32 v193, v193, v194
	v_mul_f32_e32 v194, v72, v203
	v_mul_f32_e32 v194, v194, v195
	v_cvt_pk_bf16_f32 v193, v193, v194
	v_mul_f32_e32 v194, v72, v204
	v_mul_f32_e32 v195, v72, v206
	s_waitcnt lgkmcnt(0)
	v_mul_f32_e32 v194, v194, v196
	v_mul_f32_e32 v195, v195, v197
	v_cvt_pk_bf16_f32 v194, v194, v195
	v_mul_f32_e32 v195, v72, v205
	v_mul_f32_e32 v195, v195, v198
	v_mul_f32_e32 v196, v72, v207
	v_mul_f32_e32 v196, v196, v199
	v_cvt_pk_bf16_f32 v195, v195, v196
	ds_write_b128 v165, v[192:195] offset:48
	s_waitcnt lgkmcnt(0)
	s_barrier
	global_load_dwordx4 v[80:83], v[120:121], off
	global_load_dwordx4 v[64:67], v[142:143], off offset:560
	global_load_dwordx4 v[68:71], v[142:143], off offset:544
	global_load_dwordx4 v[72:75], v[142:143], off offset:528
	global_load_dwordx4 v[76:79], v[142:143], off offset:512
	global_load_dwordx4 v[84:87], v[122:123], off
	global_load_dwordx4 v[88:91], v[124:125], off
	global_load_dwordx4 v[92:95], v[126:127], off
	global_load_dwordx4 v[60:63], v[144:145], off offset:512
	global_load_dwordx4 v[56:59], v[146:147], off offset:512
	global_load_dwordx4 v[52:55], v[144:145], off offset:576
	global_load_dwordx4 v[48:51], v[146:147], off offset:576
	global_load_dwordx4 v[44:47], v[144:145], off offset:640
	global_load_dwordx4 v[40:43], v[146:147], off offset:640
	global_load_dwordx4 v[36:39], v[144:145], off offset:704
	global_load_dwordx4 v[32:35], v[146:147], off offset:704
	ds_read_b128 v[168:171], v166 offset:32768
	ds_read_b128 v[172:175], v166 offset:32832
	ds_read_b128 v[176:179], v166 offset:32896
	ds_read_b128 v[180:183], v166 offset:32960
	ds_read_b32 v167, v158 offset:2560
	ds_read_b64_tr_b16 v[184:185], v159
	ds_read_b64_tr_b16 v[186:187], v159 offset:1088
	ds_read_b64_tr_b16 v[188:189], v159 offset:8704
	ds_read_b64_tr_b16 v[190:191], v159 offset:9792
	s_waitcnt lgkmcnt(2)
	v_mfma_f32_16x16x32_bf16 v[184:187], v[184:187], v[168:171], 0
	s_waitcnt lgkmcnt(0)
	v_mfma_f32_16x16x32_bf16 v[184:187], v[188:191], v[172:175], v[184:187]
	ds_read_b64_tr_b16 v[188:189], v159 offset:17408
	ds_read_b64_tr_b16 v[190:191], v159 offset:18496
	s_waitcnt lgkmcnt(0)
	v_mfma_f32_16x16x32_bf16 v[184:187], v[188:191], v[176:179], v[184:187]
	ds_read_b64_tr_b16 v[188:189], v159 offset:26112
	ds_read_b64_tr_b16 v[190:191], v159 offset:27200
	s_waitcnt lgkmcnt(0)
	v_mfma_f32_16x16x32_bf16 v[184:187], v[188:191], v[180:183], v[184:187]
	s_waitcnt vmcnt(27)
	v_lshlrev_b32_e32 v188, 16, v28
	v_and_b32_e32 v28, 0xffff0000, v28
	s_nop 4
	v_add_f32_e32 v184, v167, v184
	v_add_f32_e32 v185, v167, v185
	v_mul_f32_e32 v184, v184, v188
	s_waitcnt vmcnt(26)
	v_lshlrev_b32_e32 v188, 16, v24
	v_mul_f32_e32 v28, v185, v28
	v_and_b32_e32 v24, 0xffff0000, v24
	v_mul_f32_e32 v24, v28, v24
	v_lshlrev_b32_e32 v28, 16, v29
	v_add_f32_e32 v185, v167, v186
	v_mul_f32_e32 v28, v185, v28
	v_lshlrev_b32_e32 v185, 16, v25
	v_mul_f32_e32 v28, v28, v185
	v_and_b32_e32 v29, 0xffff0000, v29
	v_add_f32_e32 v185, v167, v187
	v_mul_f32_e32 v29, v185, v29
	v_and_b32_e32 v25, 0xffff0000, v25
	v_mul_f32_e32 v184, v184, v188
	v_mul_f32_e32 v25, v29, v25
	v_cvt_pk_bf16_f32 v24, v184, v24
	v_cvt_pk_bf16_f32 v25, v28, v25
	ds_read_b64_tr_b16 v[184:185], v159 offset:8
	ds_read_b64_tr_b16 v[186:187], v159 offset:1096
	ds_read_b64_tr_b16 v[188:189], v159 offset:8712
	ds_read_b64_tr_b16 v[190:191], v159 offset:9800
	s_waitcnt lgkmcnt(2)
	v_mfma_f32_16x16x32_bf16 v[184:187], v[184:187], v[168:171], 0
	v_lshlrev_b32_e32 v28, 16, v30
	s_waitcnt lgkmcnt(0)
	v_mfma_f32_16x16x32_bf16 v[184:187], v[188:191], v[172:175], v[184:187]
	ds_read_b64_tr_b16 v[188:189], v159 offset:17416
	ds_read_b64_tr_b16 v[190:191], v159 offset:18504
	s_waitcnt lgkmcnt(0)
	v_mfma_f32_16x16x32_bf16 v[184:187], v[188:191], v[176:179], v[184:187]
	ds_read_b64_tr_b16 v[188:189], v159 offset:26120
	ds_read_b64_tr_b16 v[190:191], v159 offset:27208
	s_waitcnt lgkmcnt(0)
	v_mfma_f32_16x16x32_bf16 v[184:187], v[188:191], v[180:183], v[184:187]
	s_nop 7
	v_add_f32_e32 v29, v167, v184
	v_mul_f32_e32 v28, v29, v28
	v_lshlrev_b32_e32 v29, 16, v26
	v_mul_f32_e32 v28, v28, v29
	v_and_b32_e32 v29, 0xffff0000, v30
	v_add_f32_e32 v30, v167, v185
	v_mul_f32_e32 v29, v30, v29
	v_and_b32_e32 v26, 0xffff0000, v26
	v_mul_f32_e32 v26, v29, v26
	v_lshlrev_b32_e32 v29, 16, v31
	v_add_f32_e32 v30, v167, v186
	v_mul_f32_e32 v29, v30, v29
	v_lshlrev_b32_e32 v30, 16, v27
	v_mul_f32_e32 v29, v29, v30
	v_and_b32_e32 v30, 0xffff0000, v31
	v_add_f32_e32 v31, v167, v187
	v_mul_f32_e32 v30, v31, v30
	v_and_b32_e32 v27, 0xffff0000, v27
	v_mul_f32_e32 v27, v30, v27
	v_cvt_pk_bf16_f32 v26, v28, v26
	v_cvt_pk_bf16_f32 v27, v29, v27
	ds_read_b64_tr_b16 v[28:29], v159 offset:64
	ds_read_b64_tr_b16 v[30:31], v159 offset:1152
	ds_read_b64_tr_b16 v[184:185], v159 offset:8768
	ds_read_b64_tr_b16 v[186:187], v159 offset:9856
	s_waitcnt lgkmcnt(2)
	v_mfma_f32_16x16x32_bf16 v[28:31], v[28:31], v[168:171], 0
	s_waitcnt lgkmcnt(0)
	v_mfma_f32_16x16x32_bf16 v[28:31], v[184:187], v[172:175], v[28:31]
	ds_read_b64_tr_b16 v[184:185], v159 offset:17472
	ds_read_b64_tr_b16 v[186:187], v159 offset:18560
	s_waitcnt lgkmcnt(0)
	v_mfma_f32_16x16x32_bf16 v[28:31], v[184:187], v[176:179], v[28:31]
	ds_read_b64_tr_b16 v[184:185], v159 offset:26176
	ds_read_b64_tr_b16 v[186:187], v159 offset:27264
	s_waitcnt lgkmcnt(0)
	v_mfma_f32_16x16x32_bf16 v[28:31], v[184:187], v[180:183], v[28:31]
	s_waitcnt vmcnt(25)
	v_lshlrev_b32_e32 v184, 16, v20
	v_and_b32_e32 v20, 0xffff0000, v20
	s_nop 4
	v_add_f32_e32 v28, v167, v28
	v_add_f32_e32 v29, v167, v29
	v_mul_f32_e32 v28, v28, v184
	s_waitcnt vmcnt(24)
	v_lshlrev_b32_e32 v184, 16, v16
	v_mul_f32_e32 v20, v29, v20
	v_and_b32_e32 v16, 0xffff0000, v16
	v_mul_f32_e32 v16, v20, v16
	v_lshlrev_b32_e32 v20, 16, v21
	v_add_f32_e32 v29, v167, v30
	v_mul_f32_e32 v20, v29, v20
	v_lshlrev_b32_e32 v29, 16, v17
	v_mul_f32_e32 v20, v20, v29
	v_and_b32_e32 v21, 0xffff0000, v21
	v_add_f32_e32 v29, v167, v31
	v_mul_f32_e32 v21, v29, v21
	v_and_b32_e32 v17, 0xffff0000, v17
	v_mul_f32_e32 v28, v28, v184
	v_mul_f32_e32 v17, v21, v17
	v_cvt_pk_bf16_f32 v16, v28, v16
	v_cvt_pk_bf16_f32 v17, v20, v17
	ds_read_b64_tr_b16 v[28:29], v159 offset:72
	ds_read_b64_tr_b16 v[30:31], v159 offset:1160
	ds_read_b64_tr_b16 v[184:185], v159 offset:8776
	ds_read_b64_tr_b16 v[186:187], v159 offset:9864
	s_waitcnt lgkmcnt(2)
	v_mfma_f32_16x16x32_bf16 v[28:31], v[28:31], v[168:171], 0
	v_lshlrev_b32_e32 v20, 16, v22
	s_waitcnt lgkmcnt(0)
	v_mfma_f32_16x16x32_bf16 v[28:31], v[184:187], v[172:175], v[28:31]
	ds_read_b64_tr_b16 v[184:185], v159 offset:17480
	ds_read_b64_tr_b16 v[186:187], v159 offset:18568
	s_waitcnt lgkmcnt(0)
	v_mfma_f32_16x16x32_bf16 v[28:31], v[184:187], v[176:179], v[28:31]
	ds_read_b64_tr_b16 v[184:185], v159 offset:26184
	ds_read_b64_tr_b16 v[186:187], v159 offset:27272
	s_waitcnt lgkmcnt(0)
	v_mfma_f32_16x16x32_bf16 v[28:31], v[184:187], v[180:183], v[28:31]
	s_nop 7
	v_add_f32_e32 v21, v167, v28
	v_mul_f32_e32 v20, v21, v20
	v_lshlrev_b32_e32 v21, 16, v18
	v_mul_f32_e32 v20, v20, v21
	v_and_b32_e32 v21, 0xffff0000, v22
	v_add_f32_e32 v22, v167, v29
	v_mul_f32_e32 v21, v22, v21
	v_and_b32_e32 v18, 0xffff0000, v18
	v_mul_f32_e32 v18, v21, v18
	v_lshlrev_b32_e32 v21, 16, v23
	v_add_f32_e32 v22, v167, v30
	v_mul_f32_e32 v21, v22, v21
	v_lshlrev_b32_e32 v22, 16, v19
	v_mul_f32_e32 v21, v21, v22
	v_and_b32_e32 v22, 0xffff0000, v23
	v_add_f32_e32 v23, v167, v31
	v_mul_f32_e32 v22, v23, v22
	v_and_b32_e32 v19, 0xffff0000, v19
	v_mul_f32_e32 v19, v22, v19
	v_cvt_pk_bf16_f32 v18, v20, v18
	v_cvt_pk_bf16_f32 v19, v21, v19
	ds_read_b64_tr_b16 v[20:21], v159 offset:128
	ds_read_b64_tr_b16 v[22:23], v159 offset:1216
	ds_read_b64_tr_b16 v[28:29], v159 offset:8832
	ds_read_b64_tr_b16 v[30:31], v159 offset:9920
	s_waitcnt lgkmcnt(2)
	v_mfma_f32_16x16x32_bf16 v[20:23], v[20:23], v[168:171], 0
	s_waitcnt lgkmcnt(0)
	v_mfma_f32_16x16x32_bf16 v[20:23], v[28:31], v[172:175], v[20:23]
	ds_read_b64_tr_b16 v[28:29], v159 offset:17536
	ds_read_b64_tr_b16 v[30:31], v159 offset:18624
	s_waitcnt lgkmcnt(0)
	v_mfma_f32_16x16x32_bf16 v[20:23], v[28:31], v[176:179], v[20:23]
	ds_read_b64_tr_b16 v[28:29], v159 offset:26240
	ds_read_b64_tr_b16 v[30:31], v159 offset:27328
	s_waitcnt lgkmcnt(0)
	v_mfma_f32_16x16x32_bf16 v[20:23], v[28:31], v[180:183], v[20:23]
	s_waitcnt vmcnt(23)
	v_lshlrev_b32_e32 v28, 16, v12
	v_and_b32_e32 v12, 0xffff0000, v12
	s_nop 4
	v_add_f32_e32 v20, v167, v20
	v_add_f32_e32 v21, v167, v21
	v_mul_f32_e32 v20, v20, v28
	s_waitcnt vmcnt(22)
	v_lshlrev_b32_e32 v28, 16, v8
	v_mul_f32_e32 v12, v21, v12
	v_and_b32_e32 v8, 0xffff0000, v8
	v_mul_f32_e32 v8, v12, v8
	v_lshlrev_b32_e32 v12, 16, v13
	v_add_f32_e32 v21, v167, v22
	v_mul_f32_e32 v12, v21, v12
	v_lshlrev_b32_e32 v21, 16, v9
	v_mul_f32_e32 v12, v12, v21
	v_and_b32_e32 v13, 0xffff0000, v13
	v_add_f32_e32 v21, v167, v23
	v_mul_f32_e32 v13, v21, v13
	v_and_b32_e32 v9, 0xffff0000, v9
	v_mul_f32_e32 v20, v20, v28
	v_mul_f32_e32 v9, v13, v9
	v_cvt_pk_bf16_f32 v8, v20, v8
	v_cvt_pk_bf16_f32 v9, v12, v9
	ds_read_b64_tr_b16 v[20:21], v159 offset:136
	ds_read_b64_tr_b16 v[22:23], v159 offset:1224
	ds_read_b64_tr_b16 v[28:29], v159 offset:8840
	ds_read_b64_tr_b16 v[30:31], v159 offset:9928
	s_waitcnt lgkmcnt(2)
	v_mfma_f32_16x16x32_bf16 v[20:23], v[20:23], v[168:171], 0
	v_lshlrev_b32_e32 v12, 16, v14
	s_waitcnt lgkmcnt(0)
	v_mfma_f32_16x16x32_bf16 v[20:23], v[28:31], v[172:175], v[20:23]
	ds_read_b64_tr_b16 v[28:29], v159 offset:17544
	ds_read_b64_tr_b16 v[30:31], v159 offset:18632
	s_waitcnt lgkmcnt(0)
	v_mfma_f32_16x16x32_bf16 v[20:23], v[28:31], v[176:179], v[20:23]
	ds_read_b64_tr_b16 v[28:29], v159 offset:26248
	ds_read_b64_tr_b16 v[30:31], v159 offset:27336
	s_waitcnt lgkmcnt(0)
	v_mfma_f32_16x16x32_bf16 v[20:23], v[28:31], v[180:183], v[20:23]
	s_waitcnt vmcnt(12)
	v_and_b32_e32 v29, 0xffff0000, v74
	v_lshlrev_b32_e32 v28, 16, v74
	v_and_b32_e32 v31, 0xffff0000, v75
	s_nop 3
	v_add_f32_e32 v13, v167, v20
	v_mul_f32_e32 v12, v13, v12
	v_lshlrev_b32_e32 v13, 16, v10
	v_mul_f32_e32 v12, v12, v13
	v_and_b32_e32 v13, 0xffff0000, v14
	v_add_f32_e32 v14, v167, v21
	v_mul_f32_e32 v13, v14, v13
	v_and_b32_e32 v10, 0xffff0000, v10
	v_mul_f32_e32 v10, v13, v10
	v_lshlrev_b32_e32 v13, 16, v15
	v_add_f32_e32 v14, v167, v22
	v_mul_f32_e32 v13, v14, v13
	v_lshlrev_b32_e32 v14, 16, v11
	v_mul_f32_e32 v13, v13, v14
	v_and_b32_e32 v14, 0xffff0000, v15
	v_add_f32_e32 v15, v167, v23
	v_mul_f32_e32 v14, v15, v14
	v_and_b32_e32 v11, 0xffff0000, v11
	v_mul_f32_e32 v11, v14, v11
	v_cvt_pk_bf16_f32 v10, v12, v10
	v_cvt_pk_bf16_f32 v11, v13, v11
	ds_read_b64_tr_b16 v[12:13], v159 offset:192
	ds_read_b64_tr_b16 v[14:15], v159 offset:1280
	ds_read_b64_tr_b16 v[20:21], v159 offset:8896
	ds_read_b64_tr_b16 v[22:23], v159 offset:9984
	s_waitcnt lgkmcnt(2)
	v_mfma_f32_16x16x32_bf16 v[12:15], v[12:15], v[168:171], 0
	v_lshlrev_b32_e32 v30, 16, v75
	v_lshlrev_b32_e32 v74, 16, v70
	v_and_b32_e32 v70, 0xffff0000, v70
	s_waitcnt lgkmcnt(0)
	v_mfma_f32_16x16x32_bf16 v[12:15], v[20:23], v[172:175], v[12:15]
	ds_read_b64_tr_b16 v[20:21], v159 offset:17600
	ds_read_b64_tr_b16 v[22:23], v159 offset:18688
	v_lshlrev_b32_e32 v75, 16, v71
	v_and_b32_e32 v71, 0xffff0000, v71
	s_waitcnt lgkmcnt(0)
	v_mfma_f32_16x16x32_bf16 v[12:15], v[20:23], v[176:179], v[12:15]
	ds_read_b64_tr_b16 v[20:21], v159 offset:26304
	ds_read_b64_tr_b16 v[22:23], v159 offset:27392
	s_waitcnt lgkmcnt(0)
	v_mfma_f32_16x16x32_bf16 v[12:15], v[20:23], v[180:183], v[12:15]
	v_lshlrev_b32_e32 v20, 16, v4
	v_and_b32_e32 v4, 0xffff0000, v4
	s_nop 5
	v_add_f32_e32 v12, v167, v12
	v_add_f32_e32 v13, v167, v13
	v_mul_f32_e32 v12, v12, v20
	v_lshlrev_b32_e32 v20, 16, v0
	v_mul_f32_e32 v4, v13, v4
	v_and_b32_e32 v0, 0xffff0000, v0
	v_mul_f32_e32 v0, v4, v0
	v_lshlrev_b32_e32 v4, 16, v5
	v_add_f32_e32 v13, v167, v14
	v_mul_f32_e32 v4, v13, v4
	v_lshlrev_b32_e32 v13, 16, v1
	v_mul_f32_e32 v4, v4, v13
	v_and_b32_e32 v5, 0xffff0000, v5
	v_add_f32_e32 v13, v167, v15
	v_mul_f32_e32 v5, v13, v5
	v_and_b32_e32 v1, 0xffff0000, v1
	v_mul_f32_e32 v12, v12, v20
	v_mul_f32_e32 v1, v5, v1
	v_cvt_pk_bf16_f32 v0, v12, v0
	v_cvt_pk_bf16_f32 v1, v4, v1
	ds_read_b64_tr_b16 v[12:13], v159 offset:200
	ds_read_b64_tr_b16 v[14:15], v159 offset:1288
	ds_read_b64_tr_b16 v[20:21], v159 offset:8904
	ds_read_b64_tr_b16 v[22:23], v159 offset:9992
	s_waitcnt lgkmcnt(2)
	v_mfma_f32_16x16x32_bf16 v[12:15], v[12:15], v[168:171], 0
	v_lshlrev_b32_e32 v4, 16, v6
	s_waitcnt lgkmcnt(0)
	v_mfma_f32_16x16x32_bf16 v[12:15], v[20:23], v[172:175], v[12:15]
	ds_read_b64_tr_b16 v[20:21], v159 offset:17608
	ds_read_b64_tr_b16 v[22:23], v159 offset:18696
	s_waitcnt lgkmcnt(0)
	v_mfma_f32_16x16x32_bf16 v[12:15], v[20:23], v[176:179], v[12:15]
	ds_read_b64_tr_b16 v[20:21], v159 offset:26312
	ds_read_b64_tr_b16 v[22:23], v159 offset:27400
	s_waitcnt lgkmcnt(0)
	v_mfma_f32_16x16x32_bf16 v[12:15], v[20:23], v[180:183], v[12:15]
	s_waitcnt vmcnt(11)
	v_and_b32_e32 v21, 0xffff0000, v78
	v_lshlrev_b32_e32 v20, 16, v78
	v_and_b32_e32 v23, 0xffff0000, v79
	s_nop 3
	v_add_f32_e32 v5, v167, v12
	v_mul_f32_e32 v4, v5, v4
	v_lshlrev_b32_e32 v5, 16, v2
	v_mul_f32_e32 v4, v4, v5
	v_and_b32_e32 v5, 0xffff0000, v6
	v_add_f32_e32 v6, v167, v13
	v_mul_f32_e32 v5, v6, v5
	v_and_b32_e32 v2, 0xffff0000, v2
	v_mul_f32_e32 v2, v5, v2
	v_lshlrev_b32_e32 v5, 16, v7
	v_add_f32_e32 v6, v167, v14
	v_mul_f32_e32 v5, v6, v5
	v_lshlrev_b32_e32 v6, 16, v3
	v_mul_f32_e32 v5, v5, v6
	v_and_b32_e32 v6, 0xffff0000, v7
	v_add_f32_e32 v7, v167, v15
	v_mul_f32_e32 v6, v7, v6
	v_and_b32_e32 v3, 0xffff0000, v3
	v_mul_f32_e32 v3, v6, v3
	v_cvt_pk_bf16_f32 v2, v4, v2
	v_cvt_pk_bf16_f32 v3, v5, v3
	global_store_dwordx4 v[148:149], v[24:27], off offset:256
	global_store_dwordx4 v[148:149], v[16:19], off offset:320
	global_store_dwordx4 v[148:149], v[8:11], off offset:384
	global_store_dwordx4 v[148:149], v[0:3], off offset:448
	v_and_b32_e32 v17, 0xffff0000, v76
	v_and_b32_e32 v19, 0xffff0000, v77
	v_lshlrev_b32_e32 v16, 16, v76
	v_mul_f32_e32 v0, v17, v17
	v_lshlrev_b32_e32 v18, 16, v77
	v_mul_f32_e32 v1, v19, v19
	v_fmac_f32_e32 v0, v16, v16
	v_fmac_f32_e32 v1, v18, v18
	v_add_f32_e32 v0, v0, v1
	v_mul_f32_e32 v1, v21, v21
	v_fmac_f32_e32 v1, v20, v20
	v_add_f32_e32 v0, v1, v0
	v_lshlrev_b32_e32 v22, 16, v79
	v_mul_f32_e32 v1, v23, v23
	v_fmac_f32_e32 v1, v22, v22
	v_and_b32_e32 v25, 0xffff0000, v72
	v_add_f32_e32 v0, v1, v0
	v_lshlrev_b32_e32 v24, 16, v72
	v_mul_f32_e32 v1, v25, v25
	v_fmac_f32_e32 v1, v24, v24
	v_and_b32_e32 v27, 0xffff0000, v73
	v_add_f32_e32 v0, v1, v0
	v_lshlrev_b32_e32 v26, 16, v73
	v_mul_f32_e32 v1, v27, v27
	v_fmac_f32_e32 v1, v26, v26
	v_add_f32_e32 v0, v1, v0
	v_mul_f32_e32 v1, v29, v29
	v_fmac_f32_e32 v1, v28, v28
	v_add_f32_e32 v0, v1, v0
	v_mul_f32_e32 v1, v31, v31
	v_fmac_f32_e32 v1, v30, v30
	v_lshlrev_b32_e32 v72, 16, v68
	v_and_b32_e32 v68, 0xffff0000, v68
	v_add_f32_e32 v0, v1, v0
	v_mul_f32_e32 v1, v68, v68
	v_fmac_f32_e32 v1, v72, v72
	v_lshlrev_b32_e32 v73, 16, v69
	v_and_b32_e32 v69, 0xffff0000, v69
	v_add_f32_e32 v0, v1, v0
	v_mul_f32_e32 v1, v69, v69
	v_fmac_f32_e32 v1, v73, v73
	v_add_f32_e32 v0, v1, v0
	v_mul_f32_e32 v1, v70, v70
	v_fmac_f32_e32 v1, v74, v74
	v_add_f32_e32 v0, v1, v0
	v_mul_f32_e32 v1, v71, v71
	v_fmac_f32_e32 v1, v75, v75
	v_and_b32_e32 v11, 0xffff0000, v65
	v_and_b32_e32 v10, 0xffff0000, v64
	v_add_f32_e32 v2, v1, v0
	v_lshlrev_b32_e32 v9, 16, v65
	v_lshlrev_b32_e32 v8, 16, v64
	v_pk_mul_f32 v[0:1], v[10:11], v[10:11]
	v_and_b32_e32 v15, 0xffff0000, v67
	v_pk_fma_f32 v[0:1], v[8:9], v[8:9], v[0:1]
	v_and_b32_e32 v14, 0xffff0000, v66
	v_add_f32_e32 v0, v0, v2
	v_add_f32_e32 v2, v1, v0
	v_lshlrev_b32_e32 v13, 16, v67
	v_lshlrev_b32_e32 v12, 16, v66
	v_pk_mul_f32 v[0:1], v[14:15], v[14:15]
	s_nop 0
	v_pk_fma_f32 v[0:1], v[12:13], v[12:13], v[0:1]
	global_load_dwordx4 v[208:211], v[128:129], off
	global_load_dwordx4 v[192:195], v[142:143], off offset:816
	global_load_dwordx4 v[196:199], v[142:143], off offset:800
	global_load_dwordx4 v[200:203], v[142:143], off offset:784
	global_load_dwordx4 v[204:207], v[142:143], off offset:768
	global_load_dwordx4 v[212:215], v[130:131], off
	global_load_dwordx4 v[218:221], v[132:133], off
	global_load_dwordx4 v[222:225], v[134:135], off
	s_barrier
	v_add_f32_e32 v0, v0, v2
	v_add_f32_e32 v0, v1, v0
	ds_bpermute_b32 v1, v155, v0
	s_waitcnt lgkmcnt(0)
	ds_write_b128 v160, v[80:83] offset:32768
	s_waitcnt vmcnt(22)
	ds_write_b128 v161, v[84:87] offset:32768
	s_waitcnt vmcnt(21)
	ds_write_b128 v162, v[88:91] offset:32768
	s_waitcnt vmcnt(20)
	ds_write_b128 v163, v[92:95] offset:32768
	v_add_f32_e32 v0, v0, v1
	ds_bpermute_b32 v1, v156, v0
	s_waitcnt lgkmcnt(0)
	v_add_f32_e32 v0, v0, v1
	v_fmamk_f32 v0, v0, 0x3c000000, v164
	v_rsq_f32_e32 v64, v0
	ds_read_b128 v[0:3], v157 offset:1024
	ds_read_b128 v[4:7], v157 offset:1040
	v_mul_f32_e32 v16, v64, v16
	s_waitcnt lgkmcnt(1)
	v_mul_f32_e32 v0, v0, v16
	v_mul_f32_e32 v16, v64, v17
	v_mul_f32_e32 v1, v1, v16
	v_cvt_pk_bf16_f32 v0, v0, v1
	v_mul_f32_e32 v1, v64, v18
	v_mul_f32_e32 v1, v2, v1
	v_mul_f32_e32 v2, v64, v19
	v_mul_f32_e32 v2, v3, v2
	v_cvt_pk_bf16_f32 v1, v1, v2
	v_mul_f32_e32 v2, v64, v20
	v_mul_f32_e32 v3, v64, v21
	s_waitcnt lgkmcnt(0)
	v_mul_f32_e32 v2, v4, v2
	v_mul_f32_e32 v3, v5, v3
	v_cvt_pk_bf16_f32 v2, v2, v3
	v_mul_f32_e32 v3, v64, v22
	v_mul_f32_e32 v3, v6, v3
	v_mul_f32_e32 v4, v64, v23
	v_mul_f32_e32 v4, v7, v4
	v_cvt_pk_bf16_f32 v3, v3, v4
	ds_write_b128 v165, v[0:3]
	ds_read_b128 v[0:3], v157 offset:1056
	ds_read_b128 v[4:7], v157 offset:1072
	v_mul_f32_e32 v16, v64, v24
	v_mul_f32_e32 v8, v64, v8
	s_waitcnt lgkmcnt(1)
	v_mul_f32_e32 v0, v16, v0
	v_mul_f32_e32 v16, v64, v25
	v_mul_f32_e32 v1, v16, v1
	v_cvt_pk_bf16_f32 v0, v0, v1
	v_mul_f32_e32 v1, v64, v26
	v_mul_f32_e32 v1, v1, v2
	v_mul_f32_e32 v2, v64, v27
	v_mul_f32_e32 v2, v2, v3
	v_cvt_pk_bf16_f32 v1, v1, v2
	v_mul_f32_e32 v2, v64, v28
	v_mul_f32_e32 v3, v64, v29
	s_waitcnt lgkmcnt(0)
	v_mul_f32_e32 v2, v2, v4
	v_mul_f32_e32 v3, v3, v5
	v_cvt_pk_bf16_f32 v2, v2, v3
	v_mul_f32_e32 v3, v64, v30
	v_mul_f32_e32 v3, v3, v6
	v_mul_f32_e32 v4, v64, v31
	v_mul_f32_e32 v4, v4, v7
	v_cvt_pk_bf16_f32 v3, v3, v4
	ds_write_b128 v165, v[0:3] offset:16
	ds_read_b128 v[0:3], v157 offset:1088
	ds_read_b128 v[4:7], v157 offset:1104
	v_mul_f32_e32 v16, v64, v72
	s_waitcnt lgkmcnt(1)
	v_mul_f32_e32 v0, v16, v0
	v_mul_f32_e32 v16, v64, v68
	v_mul_f32_e32 v1, v16, v1
	v_cvt_pk_bf16_f32 v0, v0, v1
	v_mul_f32_e32 v1, v64, v73
	v_mul_f32_e32 v1, v1, v2
	v_mul_f32_e32 v2, v64, v69
	v_mul_f32_e32 v2, v2, v3
	v_cvt_pk_bf16_f32 v1, v1, v2
	v_mul_f32_e32 v2, v64, v74
	v_mul_f32_e32 v3, v64, v70
	s_waitcnt lgkmcnt(0)
	v_mul_f32_e32 v2, v2, v4
	v_mul_f32_e32 v3, v3, v5
	v_cvt_pk_bf16_f32 v2, v2, v3
	v_mul_f32_e32 v3, v64, v75
	v_mul_f32_e32 v3, v3, v6
	v_mul_f32_e32 v4, v64, v71
	v_mul_f32_e32 v4, v4, v7
	v_cvt_pk_bf16_f32 v3, v3, v4
	ds_write_b128 v165, v[0:3] offset:32
	ds_read_b128 v[0:3], v157 offset:1120
	ds_read_b128 v[4:7], v157 offset:1136
	s_waitcnt lgkmcnt(1)
	v_mul_f32_e32 v0, v8, v0
	v_mul_f32_e32 v8, v64, v10
	v_mul_f32_e32 v1, v8, v1
	v_cvt_pk_bf16_f32 v0, v0, v1
	v_mul_f32_e32 v1, v64, v9
	v_mul_f32_e32 v1, v1, v2
	v_mul_f32_e32 v2, v64, v11
	v_mul_f32_e32 v2, v2, v3
	v_cvt_pk_bf16_f32 v1, v1, v2
	v_mul_f32_e32 v2, v64, v12
	v_mul_f32_e32 v3, v64, v14
	s_waitcnt lgkmcnt(0)
	v_mul_f32_e32 v2, v2, v4
	v_mul_f32_e32 v3, v3, v5
	v_cvt_pk_bf16_f32 v2, v2, v3
	v_mul_f32_e32 v3, v64, v13
	v_mul_f32_e32 v3, v3, v6
	v_mul_f32_e32 v4, v64, v15
	v_mul_f32_e32 v4, v4, v7
	v_cvt_pk_bf16_f32 v3, v3, v4
	ds_write_b128 v165, v[0:3] offset:48
	s_waitcnt lgkmcnt(0)
	s_barrier
	global_load_dwordx4 v[28:31], v[144:145], off offset:768
	global_load_dwordx4 v[24:27], v[146:147], off offset:768
	global_load_dwordx4 v[20:23], v[144:145], off offset:832
	global_load_dwordx4 v[16:19], v[146:147], off offset:832
	global_load_dwordx4 v[12:15], v[144:145], off offset:896
	global_load_dwordx4 v[8:11], v[146:147], off offset:896
	global_load_dwordx4 v[4:7], v[144:145], off offset:960
	global_load_dwordx4 v[0:3], v[146:147], off offset:960
	ds_read_b128 v[142:145], v166 offset:32768
	ds_read_b128 v[168:171], v166 offset:32832
	ds_read_b128 v[172:175], v166 offset:32896
	ds_read_b128 v[176:179], v166 offset:32960
	ds_read_b32 v146, v158 offset:3072
	ds_read_b64_tr_b16 v[180:181], v159
	ds_read_b64_tr_b16 v[182:183], v159 offset:1088
	ds_read_b64_tr_b16 v[184:185], v159 offset:8704
	ds_read_b64_tr_b16 v[186:187], v159 offset:9792
	s_waitcnt lgkmcnt(2)
	v_mfma_f32_16x16x32_bf16 v[180:183], v[180:183], v[142:145], 0
	s_waitcnt vmcnt(27)
	v_lshlrev_b32_e32 v147, 16, v60
	v_and_b32_e32 v60, 0xffff0000, v60
	s_waitcnt lgkmcnt(0)
	v_mfma_f32_16x16x32_bf16 v[180:183], v[184:187], v[168:171], v[180:183]
	ds_read_b64_tr_b16 v[184:185], v159 offset:17408
	ds_read_b64_tr_b16 v[186:187], v159 offset:18496
	s_waitcnt lgkmcnt(0)
	v_mfma_f32_16x16x32_bf16 v[180:183], v[184:187], v[172:175], v[180:183]
	ds_read_b64_tr_b16 v[184:185], v159 offset:26112
	ds_read_b64_tr_b16 v[186:187], v159 offset:27200
	s_waitcnt lgkmcnt(0)
	v_mfma_f32_16x16x32_bf16 v[180:183], v[184:187], v[176:179], v[180:183]
	s_nop 7
	v_add_f32_e32 v167, v146, v180
	v_mul_f32_e32 v147, v167, v147
	s_waitcnt vmcnt(26)
	v_lshlrev_b32_e32 v167, 16, v56
	v_mul_f32_e32 v147, v147, v167
	v_add_f32_e32 v167, v146, v181
	v_mul_f32_e32 v60, v167, v60
	v_and_b32_e32 v56, 0xffff0000, v56
	v_mul_f32_e32 v56, v60, v56
	v_lshlrev_b32_e32 v60, 16, v61
	v_add_f32_e32 v167, v146, v182
	v_mul_f32_e32 v60, v167, v60
	v_lshlrev_b32_e32 v167, 16, v57
	v_mul_f32_e32 v60, v60, v167
	v_and_b32_e32 v61, 0xffff0000, v61
	v_add_f32_e32 v167, v146, v183
	v_mul_f32_e32 v61, v167, v61
	v_and_b32_e32 v57, 0xffff0000, v57
	v_mul_f32_e32 v57, v61, v57
	v_cvt_pk_bf16_f32 v56, v147, v56
	v_cvt_pk_bf16_f32 v57, v60, v57
	ds_read_b64_tr_b16 v[180:181], v159 offset:8
	ds_read_b64_tr_b16 v[182:183], v159 offset:1096
	ds_read_b64_tr_b16 v[184:185], v159 offset:8712
	ds_read_b64_tr_b16 v[186:187], v159 offset:9800
	s_waitcnt lgkmcnt(2)
	v_mfma_f32_16x16x32_bf16 v[180:183], v[180:183], v[142:145], 0
	v_lshlrev_b32_e32 v60, 16, v62
	s_waitcnt vmcnt(25)
	v_lshlrev_b32_e32 v147, 16, v52
	v_and_b32_e32 v52, 0xffff0000, v52
	s_waitcnt lgkmcnt(0)
	v_mfma_f32_16x16x32_bf16 v[180:183], v[184:187], v[168:171], v[180:183]
	ds_read_b64_tr_b16 v[184:185], v159 offset:17416
	ds_read_b64_tr_b16 v[186:187], v159 offset:18504
	s_waitcnt lgkmcnt(0)
	v_mfma_f32_16x16x32_bf16 v[180:183], v[184:187], v[172:175], v[180:183]
	ds_read_b64_tr_b16 v[184:185], v159 offset:26120
	ds_read_b64_tr_b16 v[186:187], v159 offset:27208
	s_waitcnt lgkmcnt(0)
	v_mfma_f32_16x16x32_bf16 v[180:183], v[184:187], v[176:179], v[180:183]
	s_nop 7
	v_add_f32_e32 v61, v146, v180
	v_mul_f32_e32 v60, v61, v60
	v_lshlrev_b32_e32 v61, 16, v58
	v_mul_f32_e32 v60, v60, v61
	v_and_b32_e32 v61, 0xffff0000, v62
	v_add_f32_e32 v62, v146, v181
	v_mul_f32_e32 v61, v62, v61
	v_and_b32_e32 v58, 0xffff0000, v58
	v_mul_f32_e32 v58, v61, v58
	v_lshlrev_b32_e32 v61, 16, v63
	v_add_f32_e32 v62, v146, v182
	v_mul_f32_e32 v61, v62, v61
	v_lshlrev_b32_e32 v62, 16, v59
	v_mul_f32_e32 v61, v61, v62
	v_and_b32_e32 v62, 0xffff0000, v63
	v_add_f32_e32 v63, v146, v183
	v_mul_f32_e32 v62, v63, v62
	v_and_b32_e32 v59, 0xffff0000, v59
	v_mul_f32_e32 v59, v62, v59
	v_cvt_pk_bf16_f32 v58, v60, v58
	v_cvt_pk_bf16_f32 v59, v61, v59
	ds_read_b64_tr_b16 v[60:61], v159 offset:64
	ds_read_b64_tr_b16 v[62:63], v159 offset:1152
	ds_read_b64_tr_b16 v[180:181], v159 offset:8768
	ds_read_b64_tr_b16 v[182:183], v159 offset:9856
	s_waitcnt lgkmcnt(2)
	v_mfma_f32_16x16x32_bf16 v[60:63], v[60:63], v[142:145], 0
	s_waitcnt lgkmcnt(0)
	v_mfma_f32_16x16x32_bf16 v[60:63], v[180:183], v[168:171], v[60:63]
	ds_read_b64_tr_b16 v[180:181], v159 offset:17472
	ds_read_b64_tr_b16 v[182:183], v159 offset:18560
	s_waitcnt lgkmcnt(0)
	v_mfma_f32_16x16x32_bf16 v[60:63], v[180:183], v[172:175], v[60:63]
	ds_read_b64_tr_b16 v[180:181], v159 offset:26176
	ds_read_b64_tr_b16 v[182:183], v159 offset:27264
	s_waitcnt lgkmcnt(0)
	v_mfma_f32_16x16x32_bf16 v[60:63], v[180:183], v[176:179], v[60:63]
	s_nop 7
	v_add_f32_e32 v60, v146, v60
	v_add_f32_e32 v61, v146, v61
	v_mul_f32_e32 v60, v60, v147
	s_waitcnt vmcnt(24)
	v_lshlrev_b32_e32 v147, 16, v48
	v_mul_f32_e32 v52, v61, v52
	v_and_b32_e32 v48, 0xffff0000, v48
	v_mul_f32_e32 v48, v52, v48
	v_lshlrev_b32_e32 v52, 16, v53
	v_add_f32_e32 v61, v146, v62
	v_mul_f32_e32 v52, v61, v52
	v_lshlrev_b32_e32 v61, 16, v49
	v_mul_f32_e32 v52, v52, v61
	v_and_b32_e32 v53, 0xffff0000, v53
	v_add_f32_e32 v61, v146, v63
	v_mul_f32_e32 v53, v61, v53
	v_and_b32_e32 v49, 0xffff0000, v49
	v_mul_f32_e32 v60, v60, v147
	v_mul_f32_e32 v49, v53, v49
	v_cvt_pk_bf16_f32 v48, v60, v48
	v_cvt_pk_bf16_f32 v49, v52, v49
	ds_read_b64_tr_b16 v[60:61], v159 offset:72
	ds_read_b64_tr_b16 v[62:63], v159 offset:1160
	ds_read_b64_tr_b16 v[180:181], v159 offset:8776
	ds_read_b64_tr_b16 v[182:183], v159 offset:9864
	s_waitcnt lgkmcnt(2)
	v_mfma_f32_16x16x32_bf16 v[60:63], v[60:63], v[142:145], 0
	v_lshlrev_b32_e32 v52, 16, v54
	s_waitcnt lgkmcnt(0)
	v_mfma_f32_16x16x32_bf16 v[60:63], v[180:183], v[168:171], v[60:63]
	ds_read_b64_tr_b16 v[180:181], v159 offset:17480
	ds_read_b64_tr_b16 v[182:183], v159 offset:18568
	s_waitcnt lgkmcnt(0)
	v_mfma_f32_16x16x32_bf16 v[60:63], v[180:183], v[172:175], v[60:63]
	ds_read_b64_tr_b16 v[180:181], v159 offset:26184
	ds_read_b64_tr_b16 v[182:183], v159 offset:27272
	s_waitcnt lgkmcnt(0)
	v_mfma_f32_16x16x32_bf16 v[60:63], v[180:183], v[176:179], v[60:63]
	s_nop 7
	v_add_f32_e32 v53, v146, v60
	v_mul_f32_e32 v52, v53, v52
	v_lshlrev_b32_e32 v53, 16, v50
	v_mul_f32_e32 v52, v52, v53
	v_and_b32_e32 v53, 0xffff0000, v54
	v_add_f32_e32 v54, v146, v61
	v_mul_f32_e32 v53, v54, v53
	v_and_b32_e32 v50, 0xffff0000, v50
	v_mul_f32_e32 v50, v53, v50
	v_lshlrev_b32_e32 v53, 16, v55
	v_add_f32_e32 v54, v146, v62
	v_mul_f32_e32 v53, v54, v53
	v_lshlrev_b32_e32 v54, 16, v51
	v_mul_f32_e32 v53, v53, v54
	v_and_b32_e32 v54, 0xffff0000, v55
	v_add_f32_e32 v55, v146, v63
	v_mul_f32_e32 v54, v55, v54
	v_and_b32_e32 v51, 0xffff0000, v51
	v_mul_f32_e32 v51, v54, v51
	v_cvt_pk_bf16_f32 v50, v52, v50
	v_cvt_pk_bf16_f32 v51, v53, v51
	ds_read_b64_tr_b16 v[52:53], v159 offset:128
	ds_read_b64_tr_b16 v[54:55], v159 offset:1216
	ds_read_b64_tr_b16 v[60:61], v159 offset:8832
	ds_read_b64_tr_b16 v[62:63], v159 offset:9920
	s_waitcnt lgkmcnt(2)
	v_mfma_f32_16x16x32_bf16 v[52:55], v[52:55], v[142:145], 0
	s_waitcnt lgkmcnt(0)
	v_mfma_f32_16x16x32_bf16 v[52:55], v[60:63], v[168:171], v[52:55]
	ds_read_b64_tr_b16 v[60:61], v159 offset:17536
	ds_read_b64_tr_b16 v[62:63], v159 offset:18624
	s_waitcnt lgkmcnt(0)
	v_mfma_f32_16x16x32_bf16 v[52:55], v[60:63], v[172:175], v[52:55]
	ds_read_b64_tr_b16 v[60:61], v159 offset:26240
	ds_read_b64_tr_b16 v[62:63], v159 offset:27328
	s_waitcnt lgkmcnt(0)
	v_mfma_f32_16x16x32_bf16 v[52:55], v[60:63], v[176:179], v[52:55]
	s_waitcnt vmcnt(23)
	v_lshlrev_b32_e32 v60, 16, v44
	v_and_b32_e32 v44, 0xffff0000, v44
	s_nop 4
	v_add_f32_e32 v52, v146, v52
	v_add_f32_e32 v53, v146, v53
	v_mul_f32_e32 v52, v52, v60
	s_waitcnt vmcnt(22)
	v_lshlrev_b32_e32 v60, 16, v40
	v_mul_f32_e32 v44, v53, v44
	v_and_b32_e32 v40, 0xffff0000, v40
	v_mul_f32_e32 v40, v44, v40
	v_lshlrev_b32_e32 v44, 16, v45
	v_add_f32_e32 v53, v146, v54
	v_mul_f32_e32 v44, v53, v44
	v_lshlrev_b32_e32 v53, 16, v41
	v_mul_f32_e32 v44, v44, v53
	v_and_b32_e32 v45, 0xffff0000, v45
	v_add_f32_e32 v53, v146, v55
	v_mul_f32_e32 v45, v53, v45
	v_and_b32_e32 v41, 0xffff0000, v41
	v_mul_f32_e32 v52, v52, v60
	v_mul_f32_e32 v41, v45, v41
	v_cvt_pk_bf16_f32 v40, v52, v40
	v_cvt_pk_bf16_f32 v41, v44, v41
	ds_read_b64_tr_b16 v[52:53], v159 offset:136
	ds_read_b64_tr_b16 v[54:55], v159 offset:1224
	ds_read_b64_tr_b16 v[60:61], v159 offset:8840
	ds_read_b64_tr_b16 v[62:63], v159 offset:9928
	s_waitcnt lgkmcnt(2)
	v_mfma_f32_16x16x32_bf16 v[52:55], v[52:55], v[142:145], 0
	v_lshlrev_b32_e32 v44, 16, v46
	s_waitcnt lgkmcnt(0)
	v_mfma_f32_16x16x32_bf16 v[52:55], v[60:63], v[168:171], v[52:55]
	ds_read_b64_tr_b16 v[60:61], v159 offset:17544
	ds_read_b64_tr_b16 v[62:63], v159 offset:18632
	s_waitcnt lgkmcnt(0)
	v_mfma_f32_16x16x32_bf16 v[52:55], v[60:63], v[172:175], v[52:55]
	ds_read_b64_tr_b16 v[60:61], v159 offset:26248
	ds_read_b64_tr_b16 v[62:63], v159 offset:27336
	s_waitcnt lgkmcnt(0)
	v_mfma_f32_16x16x32_bf16 v[52:55], v[60:63], v[176:179], v[52:55]
	s_waitcnt vmcnt(12)
	v_and_b32_e32 v61, 0xffff0000, v202
	v_lshlrev_b32_e32 v60, 16, v202
	v_and_b32_e32 v63, 0xffff0000, v203
	s_nop 3
	v_add_f32_e32 v45, v146, v52
	v_mul_f32_e32 v44, v45, v44
	v_lshlrev_b32_e32 v45, 16, v42
	v_mul_f32_e32 v44, v44, v45
	v_and_b32_e32 v45, 0xffff0000, v46
	v_add_f32_e32 v46, v146, v53
	v_mul_f32_e32 v45, v46, v45
	v_and_b32_e32 v42, 0xffff0000, v42
	v_mul_f32_e32 v42, v45, v42
	v_lshlrev_b32_e32 v45, 16, v47
	v_add_f32_e32 v46, v146, v54
	v_mul_f32_e32 v45, v46, v45
	v_lshlrev_b32_e32 v46, 16, v43
	v_mul_f32_e32 v45, v45, v46
	v_and_b32_e32 v46, 0xffff0000, v47
	v_add_f32_e32 v47, v146, v55
	v_mul_f32_e32 v46, v47, v46
	v_and_b32_e32 v43, 0xffff0000, v43
	v_mul_f32_e32 v43, v46, v43
	v_cvt_pk_bf16_f32 v42, v44, v42
	v_cvt_pk_bf16_f32 v43, v45, v43
	ds_read_b64_tr_b16 v[44:45], v159 offset:192
	ds_read_b64_tr_b16 v[46:47], v159 offset:1280
	ds_read_b64_tr_b16 v[52:53], v159 offset:8896
	ds_read_b64_tr_b16 v[54:55], v159 offset:9984
	s_waitcnt lgkmcnt(2)
	v_mfma_f32_16x16x32_bf16 v[44:47], v[44:47], v[142:145], 0
	v_lshlrev_b32_e32 v62, 16, v203
	v_lshlrev_b32_e32 v202, 16, v198
	v_and_b32_e32 v198, 0xffff0000, v198
	s_waitcnt lgkmcnt(0)
	v_mfma_f32_16x16x32_bf16 v[44:47], v[52:55], v[168:171], v[44:47]
	ds_read_b64_tr_b16 v[52:53], v159 offset:17600
	ds_read_b64_tr_b16 v[54:55], v159 offset:18688
	v_lshlrev_b32_e32 v203, 16, v199
	v_and_b32_e32 v199, 0xffff0000, v199
	s_waitcnt lgkmcnt(0)
	v_mfma_f32_16x16x32_bf16 v[44:47], v[52:55], v[172:175], v[44:47]
	ds_read_b64_tr_b16 v[52:53], v159 offset:26304
	ds_read_b64_tr_b16 v[54:55], v159 offset:27392
	s_waitcnt lgkmcnt(0)
	v_mfma_f32_16x16x32_bf16 v[44:47], v[52:55], v[176:179], v[44:47]
	v_lshlrev_b32_e32 v52, 16, v36
	v_and_b32_e32 v36, 0xffff0000, v36
	s_nop 5
	v_add_f32_e32 v44, v146, v44
	v_add_f32_e32 v45, v146, v45
	v_mul_f32_e32 v44, v44, v52
	v_lshlrev_b32_e32 v52, 16, v32
	v_mul_f32_e32 v36, v45, v36
	v_and_b32_e32 v32, 0xffff0000, v32
	v_mul_f32_e32 v32, v36, v32
	v_lshlrev_b32_e32 v36, 16, v37
	v_add_f32_e32 v45, v146, v46
	v_mul_f32_e32 v36, v45, v36
	v_lshlrev_b32_e32 v45, 16, v33
	v_mul_f32_e32 v36, v36, v45
	v_and_b32_e32 v37, 0xffff0000, v37
	v_add_f32_e32 v45, v146, v47
	v_mul_f32_e32 v37, v45, v37
	v_and_b32_e32 v33, 0xffff0000, v33
	v_mul_f32_e32 v44, v44, v52
	v_mul_f32_e32 v33, v37, v33
	v_cvt_pk_bf16_f32 v32, v44, v32
	v_cvt_pk_bf16_f32 v33, v36, v33
	ds_read_b64_tr_b16 v[44:45], v159 offset:200
	ds_read_b64_tr_b16 v[46:47], v159 offset:1288
	ds_read_b64_tr_b16 v[52:53], v159 offset:8904
	ds_read_b64_tr_b16 v[54:55], v159 offset:9992
	s_waitcnt lgkmcnt(2)
	v_mfma_f32_16x16x32_bf16 v[44:47], v[44:47], v[142:145], 0
	v_lshlrev_b32_e32 v36, 16, v38
	s_waitcnt lgkmcnt(0)
	v_mfma_f32_16x16x32_bf16 v[44:47], v[52:55], v[168:171], v[44:47]
	ds_read_b64_tr_b16 v[52:53], v159 offset:17608
	ds_read_b64_tr_b16 v[54:55], v159 offset:18696
	s_waitcnt lgkmcnt(0)
	v_mfma_f32_16x16x32_bf16 v[44:47], v[52:55], v[172:175], v[44:47]
	ds_read_b64_tr_b16 v[52:53], v159 offset:26312
	ds_read_b64_tr_b16 v[54:55], v159 offset:27400
	s_waitcnt lgkmcnt(0)
	v_mfma_f32_16x16x32_bf16 v[44:47], v[52:55], v[176:179], v[44:47]
	s_waitcnt vmcnt(11)
	v_and_b32_e32 v53, 0xffff0000, v206
	v_lshlrev_b32_e32 v52, 16, v206
	v_and_b32_e32 v55, 0xffff0000, v207
	s_nop 3
	v_add_f32_e32 v37, v146, v44
	v_mul_f32_e32 v36, v37, v36
	v_lshlrev_b32_e32 v37, 16, v34
	v_mul_f32_e32 v36, v36, v37
	v_and_b32_e32 v37, 0xffff0000, v38
	v_add_f32_e32 v38, v146, v45
	v_mul_f32_e32 v37, v38, v37
	v_and_b32_e32 v34, 0xffff0000, v34
	v_mul_f32_e32 v34, v37, v34
	v_lshlrev_b32_e32 v37, 16, v39
	v_add_f32_e32 v38, v146, v46
	v_mul_f32_e32 v37, v38, v37
	v_lshlrev_b32_e32 v38, 16, v35
	v_mul_f32_e32 v37, v37, v38
	v_and_b32_e32 v38, 0xffff0000, v39
	v_add_f32_e32 v39, v146, v47
	v_mul_f32_e32 v38, v39, v38
	v_and_b32_e32 v35, 0xffff0000, v35
	v_mul_f32_e32 v35, v38, v35
	v_cvt_pk_bf16_f32 v34, v36, v34
	v_cvt_pk_bf16_f32 v35, v37, v35
	global_store_dwordx4 v[148:149], v[56:59], off offset:512
	global_store_dwordx4 v[148:149], v[48:51], off offset:576
	global_store_dwordx4 v[148:149], v[40:43], off offset:640
	global_store_dwordx4 v[148:149], v[32:35], off offset:704
	v_and_b32_e32 v49, 0xffff0000, v204
	v_and_b32_e32 v51, 0xffff0000, v205
	v_lshlrev_b32_e32 v48, 16, v204
	v_mul_f32_e32 v32, v49, v49
	v_lshlrev_b32_e32 v50, 16, v205
	v_mul_f32_e32 v33, v51, v51
	v_fmac_f32_e32 v32, v48, v48
	v_fmac_f32_e32 v33, v50, v50
	v_add_f32_e32 v32, v32, v33
	v_mul_f32_e32 v33, v53, v53
	v_fmac_f32_e32 v33, v52, v52
	v_add_f32_e32 v32, v33, v32
	v_lshlrev_b32_e32 v54, 16, v207
	v_mul_f32_e32 v33, v55, v55
	v_fmac_f32_e32 v33, v54, v54
	v_and_b32_e32 v57, 0xffff0000, v200
	v_add_f32_e32 v32, v33, v32
	v_lshlrev_b32_e32 v56, 16, v200
	v_mul_f32_e32 v33, v57, v57
	v_fmac_f32_e32 v33, v56, v56
	v_and_b32_e32 v59, 0xffff0000, v201
	v_add_f32_e32 v32, v33, v32
	v_lshlrev_b32_e32 v58, 16, v201
	v_mul_f32_e32 v33, v59, v59
	v_fmac_f32_e32 v33, v58, v58
	v_add_f32_e32 v32, v33, v32
	v_mul_f32_e32 v33, v61, v61
	v_fmac_f32_e32 v33, v60, v60
	v_add_f32_e32 v32, v33, v32
	v_mul_f32_e32 v33, v63, v63
	v_fmac_f32_e32 v33, v62, v62
	v_lshlrev_b32_e32 v200, 16, v196
	v_and_b32_e32 v196, 0xffff0000, v196
	v_add_f32_e32 v32, v33, v32
	v_mul_f32_e32 v33, v196, v196
	v_fmac_f32_e32 v33, v200, v200
	v_lshlrev_b32_e32 v201, 16, v197
	v_and_b32_e32 v197, 0xffff0000, v197
	v_add_f32_e32 v32, v33, v32
	v_mul_f32_e32 v33, v197, v197
	v_fmac_f32_e32 v33, v201, v201
	v_add_f32_e32 v32, v33, v32
	v_mul_f32_e32 v33, v198, v198
	v_fmac_f32_e32 v33, v202, v202
	v_add_f32_e32 v32, v33, v32
	v_mul_f32_e32 v33, v199, v199
	v_fmac_f32_e32 v33, v203, v203
	v_and_b32_e32 v43, 0xffff0000, v193
	v_and_b32_e32 v42, 0xffff0000, v192
	v_add_f32_e32 v34, v33, v32
	v_lshlrev_b32_e32 v41, 16, v193
	v_lshlrev_b32_e32 v40, 16, v192
	v_pk_mul_f32 v[32:33], v[42:43], v[42:43]
	v_and_b32_e32 v47, 0xffff0000, v195
	v_pk_fma_f32 v[32:33], v[40:41], v[40:41], v[32:33]
	v_and_b32_e32 v46, 0xffff0000, v194
	v_add_f32_e32 v32, v32, v34
	v_add_f32_e32 v34, v33, v32
	v_lshlrev_b32_e32 v45, 16, v195
	v_lshlrev_b32_e32 v44, 16, v194
	v_pk_mul_f32 v[32:33], v[46:47], v[46:47]
	s_nop 0
	v_pk_fma_f32 v[32:33], v[44:45], v[44:45], v[32:33]
	s_barrier
	v_add_f32_e32 v32, v32, v34
	v_add_f32_e32 v32, v33, v32
	ds_bpermute_b32 v33, v155, v32
	s_waitcnt lgkmcnt(0)
	ds_write_b128 v160, v[208:211] offset:32768
	s_waitcnt vmcnt(14)
	ds_write_b128 v161, v[212:215] offset:32768
	s_waitcnt vmcnt(13)
	ds_write_b128 v162, v[218:221] offset:32768
	s_waitcnt vmcnt(12)
	ds_write_b128 v163, v[222:225] offset:32768
	v_add_f32_e32 v32, v32, v33
	ds_bpermute_b32 v33, v156, v32
	s_waitcnt lgkmcnt(0)
	v_add_f32_e32 v32, v32, v33
	v_fmamk_f32 v32, v32, 0x3c000000, v164
	v_rsq_f32_e32 v192, v32
	ds_read_b128 v[32:35], v157 offset:1536
	ds_read_b128 v[36:39], v157 offset:1552
	v_mul_f32_e32 v48, v192, v48
	s_waitcnt lgkmcnt(1)
	v_mul_f32_e32 v32, v32, v48
	v_mul_f32_e32 v48, v192, v49
	v_mul_f32_e32 v33, v33, v48
	v_cvt_pk_bf16_f32 v32, v32, v33
	v_mul_f32_e32 v33, v192, v50
	v_mul_f32_e32 v33, v34, v33
	v_mul_f32_e32 v34, v192, v51
	v_mul_f32_e32 v34, v35, v34
	v_cvt_pk_bf16_f32 v33, v33, v34
	v_mul_f32_e32 v34, v192, v52
	v_mul_f32_e32 v35, v192, v53
	s_waitcnt lgkmcnt(0)
	v_mul_f32_e32 v34, v36, v34
	v_mul_f32_e32 v35, v37, v35
	v_cvt_pk_bf16_f32 v34, v34, v35
	v_mul_f32_e32 v35, v192, v54
	v_mul_f32_e32 v35, v38, v35
	v_mul_f32_e32 v36, v192, v55
	v_mul_f32_e32 v36, v39, v36
	v_cvt_pk_bf16_f32 v35, v35, v36
	ds_write_b128 v165, v[32:35]
	ds_read_b128 v[32:35], v157 offset:1568
	ds_read_b128 v[36:39], v157 offset:1584
	v_mul_f32_e32 v48, v192, v56
	v_mul_f32_e32 v40, v192, v40
	s_waitcnt lgkmcnt(1)
	v_mul_f32_e32 v32, v48, v32
	v_mul_f32_e32 v48, v192, v57
	v_mul_f32_e32 v33, v48, v33
	v_cvt_pk_bf16_f32 v32, v32, v33
	v_mul_f32_e32 v33, v192, v58
	v_mul_f32_e32 v33, v33, v34
	v_mul_f32_e32 v34, v192, v59
	v_mul_f32_e32 v34, v34, v35
	v_cvt_pk_bf16_f32 v33, v33, v34
	v_mul_f32_e32 v34, v192, v60
	v_mul_f32_e32 v35, v192, v61
	s_waitcnt lgkmcnt(0)
	v_mul_f32_e32 v34, v34, v36
	v_mul_f32_e32 v35, v35, v37
	v_cvt_pk_bf16_f32 v34, v34, v35
	v_mul_f32_e32 v35, v192, v62
	v_mul_f32_e32 v35, v35, v38
	v_mul_f32_e32 v36, v192, v63
	v_mul_f32_e32 v36, v36, v39
	v_cvt_pk_bf16_f32 v35, v35, v36
	ds_write_b128 v165, v[32:35] offset:16
	ds_read_b128 v[32:35], v157 offset:1600
	ds_read_b128 v[36:39], v157 offset:1616
	v_mul_f32_e32 v48, v192, v200
	s_waitcnt lgkmcnt(1)
	v_mul_f32_e32 v32, v48, v32
	v_mul_f32_e32 v48, v192, v196
	v_mul_f32_e32 v33, v48, v33
	v_cvt_pk_bf16_f32 v32, v32, v33
	v_mul_f32_e32 v33, v192, v201
	v_mul_f32_e32 v33, v33, v34
	v_mul_f32_e32 v34, v192, v197
	v_mul_f32_e32 v34, v34, v35
	v_cvt_pk_bf16_f32 v33, v33, v34
	v_mul_f32_e32 v34, v192, v202
	v_mul_f32_e32 v35, v192, v198
	s_waitcnt lgkmcnt(0)
	v_mul_f32_e32 v34, v34, v36
	v_mul_f32_e32 v35, v35, v37
	v_cvt_pk_bf16_f32 v34, v34, v35
	v_mul_f32_e32 v35, v192, v203
	v_mul_f32_e32 v35, v35, v38
	v_mul_f32_e32 v36, v192, v199
	v_mul_f32_e32 v36, v36, v39
	v_cvt_pk_bf16_f32 v35, v35, v36
	ds_write_b128 v165, v[32:35] offset:32
	ds_read_b128 v[32:35], v157 offset:1632
	ds_read_b128 v[36:39], v157 offset:1648
	s_waitcnt lgkmcnt(1)
	v_mul_f32_e32 v32, v40, v32
	v_mul_f32_e32 v40, v192, v42
	v_mul_f32_e32 v33, v40, v33
	v_cvt_pk_bf16_f32 v32, v32, v33
	v_mul_f32_e32 v33, v192, v41
	v_mul_f32_e32 v33, v33, v34
	v_mul_f32_e32 v34, v192, v43
	v_mul_f32_e32 v34, v34, v35
	v_cvt_pk_bf16_f32 v33, v33, v34
	v_mul_f32_e32 v34, v192, v44
	v_mul_f32_e32 v35, v192, v46
	s_waitcnt lgkmcnt(0)
	v_mul_f32_e32 v34, v34, v36
	v_mul_f32_e32 v35, v35, v37
	v_cvt_pk_bf16_f32 v34, v34, v35
	v_mul_f32_e32 v35, v192, v45
	v_mul_f32_e32 v35, v35, v38
	v_mul_f32_e32 v36, v192, v47
	v_mul_f32_e32 v36, v36, v39
	v_cvt_pk_bf16_f32 v35, v35, v36
	ds_write_b128 v165, v[32:35] offset:48
	s_waitcnt lgkmcnt(0)
	s_barrier
	ds_read_b128 v[32:35], v166 offset:32768
	ds_read_b128 v[36:39], v166 offset:32832
	ds_read_b128 v[40:43], v166 offset:32896
	ds_read_b128 v[44:47], v166 offset:32960
	ds_read_b32 v56, v158 offset:3584
	ds_read_b64_tr_b16 v[48:49], v159
	ds_read_b64_tr_b16 v[50:51], v159 offset:1088
	ds_read_b64_tr_b16 v[52:53], v159 offset:8704
	ds_read_b64_tr_b16 v[54:55], v159 offset:9792
	s_waitcnt lgkmcnt(2)
	v_mfma_f32_16x16x32_bf16 v[48:51], v[48:51], v[32:35], 0
	s_waitcnt lgkmcnt(0)
	v_mfma_f32_16x16x32_bf16 v[48:51], v[52:55], v[36:39], v[48:51]
	ds_read_b64_tr_b16 v[52:53], v159 offset:17408
	ds_read_b64_tr_b16 v[54:55], v159 offset:18496
	s_waitcnt lgkmcnt(0)
	v_mfma_f32_16x16x32_bf16 v[48:51], v[52:55], v[40:43], v[48:51]
	ds_read_b64_tr_b16 v[52:53], v159 offset:26112
	ds_read_b64_tr_b16 v[54:55], v159 offset:27200
	s_waitcnt lgkmcnt(0)
	v_mfma_f32_16x16x32_bf16 v[48:51], v[52:55], v[44:47], v[48:51]
	s_waitcnt vmcnt(11)
	v_lshlrev_b32_e32 v52, 16, v28
	v_and_b32_e32 v28, 0xffff0000, v28
	s_nop 4
	v_add_f32_e32 v48, v56, v48
	v_add_f32_e32 v49, v56, v49
	v_mul_f32_e32 v48, v48, v52
	s_waitcnt vmcnt(10)
	v_lshlrev_b32_e32 v52, 16, v24
	v_mul_f32_e32 v28, v49, v28
	v_and_b32_e32 v24, 0xffff0000, v24
	v_mul_f32_e32 v24, v28, v24
	v_lshlrev_b32_e32 v28, 16, v29
	v_add_f32_e32 v49, v56, v50
	v_mul_f32_e32 v28, v49, v28
	v_lshlrev_b32_e32 v49, 16, v25
	v_mul_f32_e32 v28, v28, v49
	v_and_b32_e32 v29, 0xffff0000, v29
	v_add_f32_e32 v49, v56, v51
	v_mul_f32_e32 v29, v49, v29
	v_and_b32_e32 v25, 0xffff0000, v25
	v_mul_f32_e32 v48, v48, v52
	v_mul_f32_e32 v25, v29, v25
	v_cvt_pk_bf16_f32 v24, v48, v24
	v_cvt_pk_bf16_f32 v25, v28, v25
	ds_read_b64_tr_b16 v[48:49], v159 offset:8
	ds_read_b64_tr_b16 v[50:51], v159 offset:1096
	ds_read_b64_tr_b16 v[52:53], v159 offset:8712
	ds_read_b64_tr_b16 v[54:55], v159 offset:9800
	s_waitcnt lgkmcnt(2)
	v_mfma_f32_16x16x32_bf16 v[48:51], v[48:51], v[32:35], 0
	v_lshlrev_b32_e32 v28, 16, v30
	s_waitcnt lgkmcnt(0)
	v_mfma_f32_16x16x32_bf16 v[48:51], v[52:55], v[36:39], v[48:51]
	ds_read_b64_tr_b16 v[52:53], v159 offset:17416
	ds_read_b64_tr_b16 v[54:55], v159 offset:18504
	s_waitcnt lgkmcnt(0)
	v_mfma_f32_16x16x32_bf16 v[48:51], v[52:55], v[40:43], v[48:51]
	ds_read_b64_tr_b16 v[52:53], v159 offset:26120
	ds_read_b64_tr_b16 v[54:55], v159 offset:27208
	s_waitcnt lgkmcnt(0)
	v_mfma_f32_16x16x32_bf16 v[48:51], v[52:55], v[44:47], v[48:51]
	s_nop 7
	v_add_f32_e32 v29, v56, v48
	v_mul_f32_e32 v28, v29, v28
	v_lshlrev_b32_e32 v29, 16, v26
	v_mul_f32_e32 v28, v28, v29
	v_and_b32_e32 v29, 0xffff0000, v30
	v_add_f32_e32 v30, v56, v49
	v_mul_f32_e32 v29, v30, v29
	v_and_b32_e32 v26, 0xffff0000, v26
	v_mul_f32_e32 v26, v29, v26
	v_lshlrev_b32_e32 v29, 16, v31
	v_add_f32_e32 v30, v56, v50
	v_mul_f32_e32 v29, v30, v29
	v_lshlrev_b32_e32 v30, 16, v27
	v_mul_f32_e32 v29, v29, v30
	v_and_b32_e32 v30, 0xffff0000, v31
	v_add_f32_e32 v31, v56, v51
	v_mul_f32_e32 v30, v31, v30
	v_and_b32_e32 v27, 0xffff0000, v27
	v_mul_f32_e32 v27, v30, v27
	v_cvt_pk_bf16_f32 v26, v28, v26
	v_cvt_pk_bf16_f32 v27, v29, v27
	ds_read_b64_tr_b16 v[28:29], v159 offset:64
	ds_read_b64_tr_b16 v[30:31], v159 offset:1152
	ds_read_b64_tr_b16 v[48:49], v159 offset:8768
	ds_read_b64_tr_b16 v[50:51], v159 offset:9856
	s_waitcnt lgkmcnt(2)
	v_mfma_f32_16x16x32_bf16 v[28:31], v[28:31], v[32:35], 0
	s_waitcnt lgkmcnt(0)
	v_mfma_f32_16x16x32_bf16 v[28:31], v[48:51], v[36:39], v[28:31]
	ds_read_b64_tr_b16 v[48:49], v159 offset:17472
	ds_read_b64_tr_b16 v[50:51], v159 offset:18560
	s_waitcnt lgkmcnt(0)
	v_mfma_f32_16x16x32_bf16 v[28:31], v[48:51], v[40:43], v[28:31]
	ds_read_b64_tr_b16 v[48:49], v159 offset:26176
	ds_read_b64_tr_b16 v[50:51], v159 offset:27264
	s_waitcnt lgkmcnt(0)
	v_mfma_f32_16x16x32_bf16 v[28:31], v[48:51], v[44:47], v[28:31]
	s_waitcnt vmcnt(9)
	v_lshlrev_b32_e32 v48, 16, v20
	v_and_b32_e32 v20, 0xffff0000, v20
	s_nop 4
	v_add_f32_e32 v28, v56, v28
	v_add_f32_e32 v29, v56, v29
	v_mul_f32_e32 v28, v28, v48
	s_waitcnt vmcnt(8)
	v_lshlrev_b32_e32 v48, 16, v16
	v_mul_f32_e32 v20, v29, v20
	v_and_b32_e32 v16, 0xffff0000, v16
	v_mul_f32_e32 v16, v20, v16
	v_lshlrev_b32_e32 v20, 16, v21
	v_add_f32_e32 v29, v56, v30
	v_mul_f32_e32 v20, v29, v20
	v_lshlrev_b32_e32 v29, 16, v17
	v_mul_f32_e32 v20, v20, v29
	v_and_b32_e32 v21, 0xffff0000, v21
	v_add_f32_e32 v29, v56, v31
	v_mul_f32_e32 v21, v29, v21
	v_and_b32_e32 v17, 0xffff0000, v17
	v_mul_f32_e32 v28, v28, v48
	v_mul_f32_e32 v17, v21, v17
	v_cvt_pk_bf16_f32 v16, v28, v16
	v_cvt_pk_bf16_f32 v17, v20, v17
	ds_read_b64_tr_b16 v[28:29], v159 offset:72
	ds_read_b64_tr_b16 v[30:31], v159 offset:1160
	ds_read_b64_tr_b16 v[48:49], v159 offset:8776
	ds_read_b64_tr_b16 v[50:51], v159 offset:9864
	s_waitcnt lgkmcnt(2)
	v_mfma_f32_16x16x32_bf16 v[28:31], v[28:31], v[32:35], 0
	v_lshlrev_b32_e32 v20, 16, v22
	s_waitcnt lgkmcnt(0)
	v_mfma_f32_16x16x32_bf16 v[28:31], v[48:51], v[36:39], v[28:31]
	ds_read_b64_tr_b16 v[48:49], v159 offset:17480
	ds_read_b64_tr_b16 v[50:51], v159 offset:18568
	s_waitcnt lgkmcnt(0)
	v_mfma_f32_16x16x32_bf16 v[28:31], v[48:51], v[40:43], v[28:31]
	ds_read_b64_tr_b16 v[48:49], v159 offset:26184
	ds_read_b64_tr_b16 v[50:51], v159 offset:27272
	s_waitcnt lgkmcnt(0)
	v_mfma_f32_16x16x32_bf16 v[28:31], v[48:51], v[44:47], v[28:31]
	s_nop 7
	v_add_f32_e32 v21, v56, v28
	v_mul_f32_e32 v20, v21, v20
	v_lshlrev_b32_e32 v21, 16, v18
	v_mul_f32_e32 v20, v20, v21
	v_and_b32_e32 v21, 0xffff0000, v22
	v_add_f32_e32 v22, v56, v29
	v_mul_f32_e32 v21, v22, v21
	v_and_b32_e32 v18, 0xffff0000, v18
	v_mul_f32_e32 v18, v21, v18
	v_lshlrev_b32_e32 v21, 16, v23
	v_add_f32_e32 v22, v56, v30
	v_mul_f32_e32 v21, v22, v21
	v_lshlrev_b32_e32 v22, 16, v19
	v_mul_f32_e32 v21, v21, v22
	v_and_b32_e32 v22, 0xffff0000, v23
	v_add_f32_e32 v23, v56, v31
	v_mul_f32_e32 v22, v23, v22
	v_and_b32_e32 v19, 0xffff0000, v19
	v_mul_f32_e32 v19, v22, v19
	v_cvt_pk_bf16_f32 v18, v20, v18
	v_cvt_pk_bf16_f32 v19, v21, v19
	ds_read_b64_tr_b16 v[20:21], v159 offset:128
	ds_read_b64_tr_b16 v[22:23], v159 offset:1216
	ds_read_b64_tr_b16 v[28:29], v159 offset:8832
	ds_read_b64_tr_b16 v[30:31], v159 offset:9920
	s_waitcnt lgkmcnt(2)
	v_mfma_f32_16x16x32_bf16 v[20:23], v[20:23], v[32:35], 0
	s_waitcnt lgkmcnt(0)
	v_mfma_f32_16x16x32_bf16 v[20:23], v[28:31], v[36:39], v[20:23]
	ds_read_b64_tr_b16 v[28:29], v159 offset:17536
	ds_read_b64_tr_b16 v[30:31], v159 offset:18624
	s_waitcnt lgkmcnt(0)
	v_mfma_f32_16x16x32_bf16 v[20:23], v[28:31], v[40:43], v[20:23]
	ds_read_b64_tr_b16 v[28:29], v159 offset:26240
	ds_read_b64_tr_b16 v[30:31], v159 offset:27328
	s_waitcnt lgkmcnt(0)
	v_mfma_f32_16x16x32_bf16 v[20:23], v[28:31], v[44:47], v[20:23]
	s_waitcnt vmcnt(7)
	v_lshlrev_b32_e32 v28, 16, v12
	v_and_b32_e32 v12, 0xffff0000, v12
	s_nop 4
	v_add_f32_e32 v20, v56, v20
	v_add_f32_e32 v21, v56, v21
	v_mul_f32_e32 v20, v20, v28
	s_waitcnt vmcnt(6)
	v_lshlrev_b32_e32 v28, 16, v8
	v_mul_f32_e32 v12, v21, v12
	v_and_b32_e32 v8, 0xffff0000, v8
	v_mul_f32_e32 v8, v12, v8
	v_lshlrev_b32_e32 v12, 16, v13
	v_add_f32_e32 v21, v56, v22
	v_mul_f32_e32 v12, v21, v12
	v_lshlrev_b32_e32 v21, 16, v9
	v_mul_f32_e32 v12, v12, v21
	v_and_b32_e32 v13, 0xffff0000, v13
	v_add_f32_e32 v21, v56, v23
	v_mul_f32_e32 v13, v21, v13
	v_and_b32_e32 v9, 0xffff0000, v9
	v_mul_f32_e32 v20, v20, v28
	v_mul_f32_e32 v9, v13, v9
	v_cvt_pk_bf16_f32 v8, v20, v8
	v_cvt_pk_bf16_f32 v9, v12, v9
	ds_read_b64_tr_b16 v[20:21], v159 offset:136
	ds_read_b64_tr_b16 v[22:23], v159 offset:1224
	ds_read_b64_tr_b16 v[28:29], v159 offset:8840
	ds_read_b64_tr_b16 v[30:31], v159 offset:9928
	s_waitcnt lgkmcnt(2)
	v_mfma_f32_16x16x32_bf16 v[20:23], v[20:23], v[32:35], 0
	v_lshlrev_b32_e32 v12, 16, v14
	s_waitcnt lgkmcnt(0)
	v_mfma_f32_16x16x32_bf16 v[20:23], v[28:31], v[36:39], v[20:23]
	ds_read_b64_tr_b16 v[28:29], v159 offset:17544
	ds_read_b64_tr_b16 v[30:31], v159 offset:18632
	s_waitcnt lgkmcnt(0)
	v_mfma_f32_16x16x32_bf16 v[20:23], v[28:31], v[40:43], v[20:23]
	ds_read_b64_tr_b16 v[28:29], v159 offset:26248
	ds_read_b64_tr_b16 v[30:31], v159 offset:27336
	s_waitcnt lgkmcnt(0)
	v_mfma_f32_16x16x32_bf16 v[20:23], v[28:31], v[44:47], v[20:23]
	s_nop 7
	v_add_f32_e32 v13, v56, v20
	v_mul_f32_e32 v12, v13, v12
	v_lshlrev_b32_e32 v13, 16, v10
	v_mul_f32_e32 v12, v12, v13
	v_and_b32_e32 v13, 0xffff0000, v14
	v_add_f32_e32 v14, v56, v21
	v_mul_f32_e32 v13, v14, v13
	v_and_b32_e32 v10, 0xffff0000, v10
	v_mul_f32_e32 v10, v13, v10
	v_lshlrev_b32_e32 v13, 16, v15
	v_add_f32_e32 v14, v56, v22
	v_mul_f32_e32 v13, v14, v13
	v_lshlrev_b32_e32 v14, 16, v11
	v_mul_f32_e32 v13, v13, v14
	v_and_b32_e32 v14, 0xffff0000, v15
	v_add_f32_e32 v15, v56, v23
	v_mul_f32_e32 v14, v15, v14
	v_and_b32_e32 v11, 0xffff0000, v11
	v_mul_f32_e32 v11, v14, v11
	v_cvt_pk_bf16_f32 v10, v12, v10
	v_cvt_pk_bf16_f32 v11, v13, v11
	ds_read_b64_tr_b16 v[12:13], v159 offset:192
	ds_read_b64_tr_b16 v[14:15], v159 offset:1280
	ds_read_b64_tr_b16 v[20:21], v159 offset:8896
	ds_read_b64_tr_b16 v[22:23], v159 offset:9984
	s_waitcnt lgkmcnt(2)
	v_mfma_f32_16x16x32_bf16 v[12:15], v[12:15], v[32:35], 0
	s_waitcnt lgkmcnt(0)
	v_mfma_f32_16x16x32_bf16 v[12:15], v[20:23], v[36:39], v[12:15]
	ds_read_b64_tr_b16 v[20:21], v159 offset:17600
	ds_read_b64_tr_b16 v[22:23], v159 offset:18688
	s_waitcnt lgkmcnt(0)
	v_mfma_f32_16x16x32_bf16 v[12:15], v[20:23], v[40:43], v[12:15]
	ds_read_b64_tr_b16 v[20:21], v159 offset:26304
	ds_read_b64_tr_b16 v[22:23], v159 offset:27392
	s_waitcnt lgkmcnt(0)
	v_mfma_f32_16x16x32_bf16 v[12:15], v[20:23], v[44:47], v[12:15]
	s_waitcnt vmcnt(5)
	v_lshlrev_b32_e32 v20, 16, v4
	v_and_b32_e32 v4, 0xffff0000, v4
	s_nop 4
	v_add_f32_e32 v12, v56, v12
	v_add_f32_e32 v13, v56, v13
	v_mul_f32_e32 v12, v12, v20
	s_waitcnt vmcnt(4)
	v_lshlrev_b32_e32 v20, 16, v0
	v_mul_f32_e32 v4, v13, v4
	v_and_b32_e32 v0, 0xffff0000, v0
	v_mul_f32_e32 v0, v4, v0
	v_lshlrev_b32_e32 v4, 16, v5
	v_add_f32_e32 v13, v56, v14
	v_mul_f32_e32 v4, v13, v4
	v_lshlrev_b32_e32 v13, 16, v1
	v_mul_f32_e32 v4, v4, v13
	v_and_b32_e32 v5, 0xffff0000, v5
	v_add_f32_e32 v13, v56, v15
	v_mul_f32_e32 v5, v13, v5
	v_and_b32_e32 v1, 0xffff0000, v1
	v_mul_f32_e32 v12, v12, v20
	v_mul_f32_e32 v1, v5, v1
	v_cvt_pk_bf16_f32 v0, v12, v0
	v_cvt_pk_bf16_f32 v1, v4, v1
	ds_read_b64_tr_b16 v[12:13], v159 offset:200
	ds_read_b64_tr_b16 v[14:15], v159 offset:1288
	ds_read_b64_tr_b16 v[20:21], v159 offset:8904
	ds_read_b64_tr_b16 v[22:23], v159 offset:9992
	s_waitcnt lgkmcnt(2)
	v_mfma_f32_16x16x32_bf16 v[12:15], v[12:15], v[32:35], 0
	v_lshlrev_b32_e32 v4, 16, v6
	s_waitcnt lgkmcnt(0)
	v_mfma_f32_16x16x32_bf16 v[12:15], v[20:23], v[36:39], v[12:15]
	ds_read_b64_tr_b16 v[20:21], v159 offset:17608
	ds_read_b64_tr_b16 v[22:23], v159 offset:18696
	s_waitcnt lgkmcnt(0)
	v_mfma_f32_16x16x32_bf16 v[12:15], v[20:23], v[40:43], v[12:15]
	ds_read_b64_tr_b16 v[20:21], v159 offset:26312
	ds_read_b64_tr_b16 v[22:23], v159 offset:27400
	s_waitcnt lgkmcnt(0)
	v_mfma_f32_16x16x32_bf16 v[12:15], v[20:23], v[44:47], v[12:15]
	s_nop 7
	v_add_f32_e32 v5, v56, v12
	v_mul_f32_e32 v4, v5, v4
	v_lshlrev_b32_e32 v5, 16, v2
	v_mul_f32_e32 v4, v4, v5
	v_and_b32_e32 v5, 0xffff0000, v6
	v_add_f32_e32 v6, v56, v13
	v_mul_f32_e32 v5, v6, v5
	v_and_b32_e32 v2, 0xffff0000, v2
	v_mul_f32_e32 v2, v5, v2
	v_lshlrev_b32_e32 v5, 16, v7
	v_add_f32_e32 v6, v56, v14
	v_mul_f32_e32 v5, v6, v5
	v_lshlrev_b32_e32 v6, 16, v3
	v_mul_f32_e32 v5, v5, v6
	v_and_b32_e32 v6, 0xffff0000, v7
	v_add_f32_e32 v7, v56, v15
	v_mul_f32_e32 v6, v7, v6
	v_and_b32_e32 v3, 0xffff0000, v3
	v_mul_f32_e32 v3, v6, v3
	v_cvt_pk_bf16_f32 v2, v4, v2
	v_cvt_pk_bf16_f32 v3, v5, v3
	global_store_dwordx4 v[148:149], v[24:27], off offset:768
	global_store_dwordx4 v[148:149], v[16:19], off offset:832
	global_store_dwordx4 v[148:149], v[8:11], off offset:896
	global_store_dwordx4 v[148:149], v[0:3], off offset:960
	s_cbranch_scc1 .LBB0_421

.LBB0_450:
	s_add_i32 s84, s71, 1
	s_mul_i32 s84, s84, s66
	s_add_i32 s84, s84, s65
	s_ashr_i32 s85, s84, 1
	s_and_b32 s85, s85, -8
	s_or_b32 s85, s85, s64
	s_cmp_gt_i32 s85, 63
	s_cbranch_scc1 .Latt_qpf_skip
	s_ashr_i32 s85, s84, 4
	s_mul_hi_i32 s89, s85, 0x1100
	s_mul_i32 s88, s85, 0x1100
	s_lshl_b32 s90, s84, 2
	s_and_b32 s90, s90, 60
	s_lshl_b32 s90, s90, 6
	s_mov_b32 s87, 0
	v_or_b32_e32 v188, s88, v216
	v_mov_b32_e32 v189, s89
	s_mov_b32 s86, s90
	v_lshl_add_u64 v[190:191], v[188:189], 0, s[86:87]
	v_lshlrev_b64 v[190:191], 10, v[190:191]
	v_lshl_add_u64 v[190:191], v[218:219], 0, v[190:191]
	global_load_dwordx4 v[132:135], v[190:191], off
	global_load_dwordx4 v[136:139], v[190:191], off offset:64
	s_or_b32 s86, s90, 0x40
	v_lshl_add_u64 v[190:191], v[188:189], 0, s[86:87]
	v_lshlrev_b64 v[190:191], 10, v[190:191]
	v_lshl_add_u64 v[190:191], v[218:219], 0, v[190:191]
	global_load_dwordx4 v[140:143], v[190:191], off
	global_load_dwordx4 v[144:147], v[190:191], off offset:64
	s_or_b32 s86, s90, 0x80
	v_lshl_add_u64 v[190:191], v[188:189], 0, s[86:87]
	v_lshlrev_b64 v[190:191], 10, v[190:191]
	v_lshl_add_u64 v[190:191], v[218:219], 0, v[190:191]
	global_load_dwordx4 v[148:151], v[190:191], off
	global_load_dwordx4 v[152:155], v[190:191], off offset:64
	s_or_b32 s86, s90, 0xc0
	v_lshl_add_u64 v[190:191], v[188:189], 0, s[86:87]
	v_lshlrev_b64 v[190:191], 10, v[190:191]
	v_lshl_add_u64 v[190:191], v[218:219], 0, v[190:191]
	global_load_dwordx4 v[156:159], v[190:191], off
	global_load_dwordx4 v[160:163], v[190:191], off offset:64
	s_ashr_i32 s92, s84, 4
	s_lshl_b32 s95, s84, 2
	s_and_b32 s95, s95, 60
	v_bfe_u32 v164, v226, 2, 3
	v_lshrrev_b32_e32 v165, 5, v226
	v_lshl_add_u32 v164, v164, 3, v165
	v_and_b32_e32 v166, 3, v226
	v_lshlrev_b32_e32 v166, 4, v166
	v_lshl_add_u32 v241, v164, 10, v166
	v_bfe_u32 v164, v226, 2, 2
	v_lshrrev_b32_e32 v165, 4, v226
	v_lshl_add_u32 v164, v164, 3, v165
	v_mul_u32_u24_e32 v164, 0x2200, v164
	v_add_u32_e32 v255, v164, v166
	v_readfirstlane_b32 s21, v231
	s_nop 3
	s_sub_u32 s21, s21, 0x8000
	s_lshr_b32 s84, s21, 13
	s_lshl_b32 s94, s84, 10
	s_mul_i32 s22, s92, 0x220000
	s_or_b32 s22, s22, s72
	s_lshl_b32 s22, s22, 1
	s_lshr_b32 s20, s84, 2
	s_lshl_b32 s20, s20, 12
	s_and_b32 s21, s84, 1
	s_lshl_b32 s21, s21, 11
	s_add_u32 s20, s20, s21
	s_bfe_u32 s21, s84, 0x10001
	s_lshl_b32 s21, s21, 6
	s_add_u32 s20, s20, s21
	s_add_u32 s61, s20, s22
	s_lshl_b32 s22, s92, 3
	s_or_b32 s22, s22, s64
	s_mul_i32 s22, s22, 0x88000
	s_lshr_b32 s20, s84, 2
	s_mul_i32 s20, s20, 0x44000
	s_bfe_u32 s21, s84, 0x10001
	s_mul_i32 s21, s21, 0x8800
	s_add_u32 s20, s20, s21
	s_and_b32 s21, s84, 1
	s_lshl_b32 s21, s21, 6
	s_add_u32 s20, s20, s21
	s_add_u32 s62, s20, s22
	s_lshr_b32 s20, s95, 2
	s_max_u32 s87, s95, 4
	s_sub_u32 s87, s87, 4
	s_and_b32 s86, s20, 1
	s_lshl_b32 s22, s20, 2
	s_sub_i32 s22, s22, 8
	s_max_i32 s22, s22, 0
	s_sub_i32 s22, s87, s22
	s_cmp_eq_u32 s86, 1
	s_cselect_b32 s60, s22, 0
	s_sub_i32 s93, s87, s60
	s_and_b32 s20, s20, 14
	s_cmp_eq_u32 s20, 0
	s_cselect_b32 s22, 11, 15
	s_cmp_eq_u32 s20, 14
	s_cselect_b32 s88, 12, s22
	s_mov_b32 s42, s26
	s_mov_b32 s43, s27
	s_add_u32 s20, s93, 0
	s_mov_b32 s87, 0x18000
	s_lshl_b32 s21, s20, 16
	s_add_u32 s21, s21, s61
	s_lshl_b32 s22, s20, 7
	s_add_u32 s22, s22, s62
	s_add_u32 m0, s87, s94
	s_add_u32 s84, s87, s94
	s_add_u32 s84, s84, 0x2000
	buffer_load_dwordx4 v241, s[24:27], s21 offen lds
	s_mov_b32 m0, s84
	s_nop 0
	buffer_load_dwordx4 v255, s[40:43], s22 offen lds
	s_add_u32 s20, s93, 1
	s_mov_b32 s87, 0x1c000
	s_lshl_b32 s21, s20, 16
	s_add_u32 s21, s21, s61
	s_lshl_b32 s22, s20, 7
	s_add_u32 s22, s22, s62
	s_add_u32 m0, s87, s94
	s_add_u32 s84, s87, s94
	s_add_u32 s84, s84, 0x2000
	buffer_load_dwordx4 v241, s[24:27], s21 offen lds
	s_mov_b32 m0, s84
	s_nop 0
	buffer_load_dwordx4 v255, s[40:43], s22 offen lds
	s_add_u32 s20, s93, 2
	s_mov_b32 s87, 0x20010
	s_lshl_b32 s21, s20, 16
	s_add_u32 s21, s21, s61
	s_lshl_b32 s22, s20, 7
	s_add_u32 s22, s22, s62
	s_add_u32 m0, s87, s94
	s_add_u32 s84, s87, s94
	s_add_u32 s84, s84, 0x2000
	buffer_load_dwordx4 v241, s[24:27], s21 offen lds
	s_mov_b32 m0, s84
	s_nop 0
	buffer_load_dwordx4 v255, s[40:43], s22 offen lds
	s_mov_b32 s20, 64
	s_mov_b32 s87, 0x8000
	s_lshl_b32 s21, s20, 16
	s_add_u32 s21, s21, s61
	s_lshl_b32 s22, s20, 7
	s_add_u32 s22, s22, s62
	s_add_u32 m0, s87, s94
	s_add_u32 s84, s87, s94
	s_add_u32 s84, s84, 0x2000
	buffer_load_dwordx4 v241, s[24:27], s21 offen lds
	s_mov_b32 m0, s84
	s_nop 0
	buffer_load_dwordx4 v255, s[40:43], s22 offen lds
	s_mov_b32 s20, 65
	s_mov_b32 s87, 0xc000
	s_lshl_b32 s21, s20, 16
	s_add_u32 s21, s21, s61
	s_lshl_b32 s22, s20, 7
	s_add_u32 s22, s22, s62
	s_add_u32 m0, s87, s94
	s_add_u32 s84, s87, s94
	s_add_u32 s84, s84, 0x2000
	buffer_load_dwordx4 v241, s[24:27], s21 offen lds
	s_mov_b32 m0, s84
	s_nop 0
	buffer_load_dwordx4 v255, s[40:43], s22 offen lds
	s_mov_b32 s20, 66
	s_mov_b32 s87, 0x10000
	s_lshl_b32 s21, s20, 16
	s_add_u32 s21, s21, s61
	s_lshl_b32 s22, s20, 7
	s_add_u32 s22, s22, s62
	s_add_u32 m0, s87, s94
	s_add_u32 s84, s87, s94
	s_add_u32 s84, s84, 0x2000
	buffer_load_dwordx4 v241, s[24:27], s21 offen lds
	s_mov_b32 m0, s84
	s_nop 0
	buffer_load_dwordx4 v255, s[40:43], s22 offen lds
	s_mov_b32 s20, 67
	s_mov_b32 s87, 0x14000
	s_lshl_b32 s21, s20, 16
	s_add_u32 s21, s21, s61
	s_lshl_b32 s22, s20, 7
	s_add_u32 s22, s22, s62
	s_add_u32 m0, s87, s94
	s_add_u32 s84, s87, s94
	s_add_u32 s84, s84, 0x2000
	buffer_load_dwordx4 v241, s[24:27], s21 offen lds
	s_mov_b32 m0, s84
	s_nop 0
	buffer_load_dwordx4 v255, s[40:43], s22 offen lds

.LBB0_456:
	s_ashr_i32 s58, s4, 4
	s_lshl_b32 s0, s4, 2
	s_mul_hi_i32 s73, s58, 0x1100
	s_mul_i32 s74, s58, 0x1100
	s_and_b32 s5, s0, 60
	v_mov_b32_e32 v3, s73
	v_or_b32_e32 v2, s74, v216
	s_lshl_b32 s36, s5, 6
	v_lshl_add_u64 v[4:5], v[2:3], 0, s[36:37]
	v_lshlrev_b64 v[4:5], 10, v[4:5]
	v_lshl_add_u64 v[12:13], v[218:219], 0, v[4:5]
	s_mov_b32 s55, s37
	s_or_b32 s54, s36, 64
	s_waitcnt vmcnt(22)
	v_mov_b32_e32 v4, v132
	v_mov_b32_e32 v5, v133
	v_mov_b32_e32 v6, v134
	v_mov_b32_e32 v7, v135
	v_mov_b32_e32 v8, v136
	v_mov_b32_e32 v9, v137
	v_mov_b32_e32 v10, v138
	v_mov_b32_e32 v11, v139
	v_lshl_add_u64 v[12:13], v[2:3], 0, s[54:55]
	v_lshlrev_b64 v[12:13], 10, v[12:13]
	v_lshl_add_u64 v[20:21], v[218:219], 0, v[12:13]
	v_mov_b32_e32 v12, v140
	v_mov_b32_e32 v13, v141
	v_mov_b32_e32 v14, v142
	v_mov_b32_e32 v15, v143
	v_mov_b32_e32 v16, v144
	v_mov_b32_e32 v17, v145
	v_mov_b32_e32 v18, v146
	v_mov_b32_e32 v19, v147
	s_mov_b32 s51, s37
	s_or_b32 s50, s36, 0x80
	v_lshl_add_u64 v[20:21], v[2:3], 0, s[50:51]
	v_lshlrev_b64 v[20:21], 10, v[20:21]
	v_lshl_add_u64 v[24:25], v[218:219], 0, v[20:21]
	v_mov_b32_e32 v20, v148
	v_mov_b32_e32 v21, v149
	v_mov_b32_e32 v22, v150
	v_mov_b32_e32 v23, v151
	s_nop 0
	v_mov_b32_e32 v24, v152
	v_mov_b32_e32 v25, v153
	v_mov_b32_e32 v26, v154
	v_mov_b32_e32 v27, v155
	v_sub_u32_e64 v1, s5, 1 clamp
	s_or_b32 s56, s36, 0xc0
	s_mov_b32 s57, s37
	v_readfirstlane_b32 s0, v1
	v_lshl_add_u64 v[2:3], v[2:3], 0, s[56:57]
	v_lshlrev_b64 v[2:3], 10, v[2:3]
	v_lshl_add_u64 v[2:3], v[218:219], 0, v[2:3]
	s_max_u32 s75, s5, 4
	s_min_u32 s0, s0, 56
	s_sub_i32 s83, s0, s75
	s_mul_i32 s0, s58, 0x220000
	s_or_b32 s7, s0, s72
	s_lshl_b32 s0, s58, 3
	s_add_i32 s76, s83, 12
	s_or_b32 s82, s0, s64
	s_add_i32 s80, s83, 19
	s_cmp_lt_i32 s83, -11
	s_mov_b64 s[0:1], -1
	v_lshlrev_b32_e32 v1, 16, v4
	v_and_b32_e32 v4, 0xffff0000, v4
	v_lshlrev_b32_e32 v28, 16, v8
	v_and_b32_e32 v8, 0xffff0000, v8
	v_lshlrev_b32_e32 v29, 16, v5
	v_and_b32_e32 v5, 0xffff0000, v5
	v_lshlrev_b32_e32 v30, 16, v9
	v_and_b32_e32 v9, 0xffff0000, v9
	v_lshlrev_b32_e32 v31, 16, v6
	v_and_b32_e32 v6, 0xffff0000, v6
	v_lshlrev_b32_e32 v32, 16, v10
	v_and_b32_e32 v10, 0xffff0000, v10
	v_lshlrev_b32_e32 v33, 16, v7
	v_and_b32_e32 v7, 0xffff0000, v7
	v_lshlrev_b32_e32 v34, 16, v11
	v_and_b32_e32 v11, 0xffff0000, v11
	v_mul_f32_e32 v4, v4, v4
	v_mul_f32_e32 v8, v8, v8
	v_mul_f32_e32 v5, v5, v5
	v_mul_f32_e32 v9, v9, v9
	v_mul_f32_e32 v6, v6, v6
	v_mul_f32_e32 v10, v10, v10
	v_mul_f32_e32 v7, v7, v7
	v_mul_f32_e32 v11, v11, v11
	v_fmac_f32_e32 v4, v1, v1
	v_fmac_f32_e32 v8, v28, v28
	v_fmac_f32_e32 v5, v29, v29
	v_fmac_f32_e32 v9, v30, v30
	v_fmac_f32_e32 v6, v31, v31
	v_fmac_f32_e32 v10, v32, v32
	v_fmac_f32_e32 v7, v33, v33
	v_fmac_f32_e32 v11, v34, v34
	v_add_f32_e32 v4, v4, v8
	v_add_f32_e32 v5, v5, v9
	v_add_f32_e32 v6, v6, v10
	v_add_f32_e32 v7, v7, v11
	v_mov_b32_e32 v8, v156
	v_mov_b32_e32 v9, v157
	v_mov_b32_e32 v10, v158
	v_mov_b32_e32 v11, v159
	v_mov_b32_e32 v28, v160
	v_mov_b32_e32 v29, v161
	v_mov_b32_e32 v30, v162
	v_mov_b32_e32 v31, v163
	s_cmp_eq_u32 s71, 0
	s_cbranch_scc0 .Latt_early_skip
	v_bfe_u32 v164, v226, 2, 3
	v_lshrrev_b32_e32 v165, 5, v226
	v_lshl_add_u32 v164, v164, 3, v165
	v_and_b32_e32 v166, 3, v226
	v_lshlrev_b32_e32 v166, 4, v166
	v_lshl_add_u32 v241, v164, 10, v166
	v_bfe_u32 v164, v226, 2, 2
	v_lshrrev_b32_e32 v165, 4, v226
	v_lshl_add_u32 v164, v164, 3, v165
	v_mul_u32_u24_e32 v164, 0x2200, v164
	v_add_u32_e32 v255, v164, v166
	v_readfirstlane_b32 s21, v231
	s_nop 3
	s_sub_u32 s21, s21, 0x8000
	s_lshr_b32 s84, s21, 13
	s_lshl_b32 s94, s84, 10
	s_mul_i32 s22, s58, 0x220000
	s_or_b32 s22, s22, s72
	s_lshl_b32 s22, s22, 1
	s_lshr_b32 s20, s84, 2
	s_lshl_b32 s20, s20, 12
	s_and_b32 s21, s84, 1
	s_lshl_b32 s21, s21, 11
	s_add_u32 s20, s20, s21
	s_bfe_u32 s21, s84, 0x10001
	s_lshl_b32 s21, s21, 6
	s_add_u32 s20, s20, s21
	s_add_u32 s61, s20, s22
	s_lshl_b32 s22, s58, 3
	s_or_b32 s22, s22, s64
	s_mul_i32 s22, s22, 0x88000
	s_lshr_b32 s20, s84, 2
	s_mul_i32 s20, s20, 0x44000
	s_bfe_u32 s21, s84, 0x10001
	s_mul_i32 s21, s21, 0x8800
	s_add_u32 s20, s20, s21
	s_and_b32 s21, s84, 1
	s_lshl_b32 s21, s21, 6
	s_add_u32 s20, s20, s21
	s_add_u32 s62, s20, s22
	s_lshr_b32 s20, s5, 2
	s_max_u32 s87, s5, 4
	s_sub_u32 s87, s87, 4
	s_and_b32 s86, s20, 1
	s_lshl_b32 s22, s20, 2
	s_sub_i32 s22, s22, 8
	s_max_i32 s22, s22, 0
	s_sub_i32 s22, s87, s22
	s_cmp_eq_u32 s86, 1
	s_cselect_b32 s60, s22, 0
	s_sub_i32 s93, s87, s60
	s_and_b32 s20, s20, 14
	s_cmp_eq_u32 s20, 0
	s_cselect_b32 s22, 11, 15
	s_cmp_eq_u32 s20, 14
	s_cselect_b32 s88, 12, s22
	s_mov_b32 s42, s26
	s_mov_b32 s43, s27
	s_add_u32 s20, s93, 0
	s_mov_b32 s87, 0x18000
	s_lshl_b32 s21, s20, 16
	s_add_u32 s21, s21, s61
	s_lshl_b32 s22, s20, 7
	s_add_u32 s22, s22, s62
	s_add_u32 m0, s87, s94
	s_add_u32 s84, s87, s94
	s_add_u32 s84, s84, 0x2000
	buffer_load_dwordx4 v241, s[24:27], s21 offen lds
	s_mov_b32 m0, s84
	s_nop 0
	buffer_load_dwordx4 v255, s[40:43], s22 offen lds
	s_add_u32 s20, s93, 1
	s_mov_b32 s87, 0x1c000
	s_lshl_b32 s21, s20, 16
	s_add_u32 s21, s21, s61
	s_lshl_b32 s22, s20, 7
	s_add_u32 s22, s22, s62
	s_add_u32 m0, s87, s94
	s_add_u32 s84, s87, s94
	s_add_u32 s84, s84, 0x2000
	buffer_load_dwordx4 v241, s[24:27], s21 offen lds
	s_mov_b32 m0, s84
	s_nop 0
	buffer_load_dwordx4 v255, s[40:43], s22 offen lds
	s_add_u32 s20, s93, 2
	s_mov_b32 s87, 0x20010
	s_lshl_b32 s21, s20, 16
	s_add_u32 s21, s21, s61
	s_lshl_b32 s22, s20, 7
	s_add_u32 s22, s22, s62
	s_add_u32 m0, s87, s94
	s_add_u32 s84, s87, s94
	s_add_u32 s84, s84, 0x2000
	buffer_load_dwordx4 v241, s[24:27], s21 offen lds
	s_mov_b32 m0, s84
	s_nop 0
	buffer_load_dwordx4 v255, s[40:43], s22 offen lds
	s_mov_b32 s20, 64
	s_mov_b32 s87, 0x8000
	s_lshl_b32 s21, s20, 16
	s_add_u32 s21, s21, s61
	s_lshl_b32 s22, s20, 7
	s_add_u32 s22, s22, s62
	s_add_u32 m0, s87, s94
	s_add_u32 s84, s87, s94
	s_add_u32 s84, s84, 0x2000
	buffer_load_dwordx4 v241, s[24:27], s21 offen lds
	s_mov_b32 m0, s84
	s_nop 0
	buffer_load_dwordx4 v255, s[40:43], s22 offen lds
	s_mov_b32 s20, 65
	s_mov_b32 s87, 0xc000
	s_lshl_b32 s21, s20, 16
	s_add_u32 s21, s21, s61
	s_lshl_b32 s22, s20, 7
	s_add_u32 s22, s22, s62
	s_add_u32 m0, s87, s94
	s_add_u32 s84, s87, s94
	s_add_u32 s84, s84, 0x2000
	buffer_load_dwordx4 v241, s[24:27], s21 offen lds
	s_mov_b32 m0, s84
	s_nop 0
	buffer_load_dwordx4 v255, s[40:43], s22 offen lds
	s_mov_b32 s20, 66
	s_mov_b32 s87, 0x10000
	s_lshl_b32 s21, s20, 16
	s_add_u32 s21, s21, s61
	s_lshl_b32 s22, s20, 7
	s_add_u32 s22, s22, s62
	s_add_u32 m0, s87, s94
	s_add_u32 s84, s87, s94
	s_add_u32 s84, s84, 0x2000
	buffer_load_dwordx4 v241, s[24:27], s21 offen lds
	s_mov_b32 m0, s84
	s_nop 0
	buffer_load_dwordx4 v255, s[40:43], s22 offen lds
	s_mov_b32 s20, 67
	s_mov_b32 s87, 0x14000
	s_lshl_b32 s21, s20, 16
	s_add_u32 s21, s21, s61
	s_lshl_b32 s22, s20, 7
	s_add_u32 s22, s22, s62
	s_add_u32 m0, s87, s94
	s_add_u32 s84, s87, s94
	s_add_u32 s84, s84, 0x2000
	buffer_load_dwordx4 v241, s[24:27], s21 offen lds
	s_mov_b32 m0, s84
	s_nop 0
	buffer_load_dwordx4 v255, s[40:43], s22 offen lds
.Latt_early_skip:
	v_lshlrev_b32_e32 v35, 16, v12
	v_and_b32_e32 v12, 0xffff0000, v12
	v_lshlrev_b32_e32 v36, 16, v16
	v_and_b32_e32 v16, 0xffff0000, v16
	v_mul_f32_e32 v1, v12, v12
	v_mul_f32_e32 v12, v16, v16
	v_lshlrev_b32_e32 v37, 16, v13
	v_and_b32_e32 v13, 0xffff0000, v13
	v_lshlrev_b32_e32 v38, 16, v17
	v_and_b32_e32 v17, 0xffff0000, v17
	v_fmac_f32_e32 v1, v35, v35
	v_fmac_f32_e32 v12, v36, v36
	v_add_f32_e32 v4, v4, v5
	v_mul_f32_e32 v13, v13, v13
	v_add_f32_e32 v5, v1, v12
	v_add_f32_e32 v1, v6, v4
	v_mul_f32_e32 v6, v17, v17
	v_fmac_f32_e32 v13, v37, v37
	v_fmac_f32_e32 v6, v38, v38
	v_add_f32_e32 v2, v13, v6
	v_add_f32_e32 v2, v5, v2
	v_and_b32_e32 v5, 0xffff0000, v14
	v_add_f32_e32 v1, v7, v1
	v_lshlrev_b32_e32 v3, 16, v14
	v_and_b32_e32 v7, 0xffff0000, v18
	v_mul_f32_e32 v5, v5, v5
	v_lshlrev_b32_e32 v6, 16, v18
	v_fmac_f32_e32 v5, v3, v3
	v_mul_f32_e32 v3, v7, v7
	v_fmac_f32_e32 v3, v6, v6
	v_add_f32_e32 v3, v5, v3
	v_and_b32_e32 v5, 0xffff0000, v15
	v_add_f32_e32 v2, v3, v2
	v_lshlrev_b32_e32 v3, 16, v15
	v_and_b32_e32 v7, 0xffff0000, v19
	v_mul_f32_e32 v5, v5, v5
	v_lshlrev_b32_e32 v6, 16, v19
	v_fmac_f32_e32 v5, v3, v3
	v_mul_f32_e32 v3, v7, v7
	v_fmac_f32_e32 v3, v6, v6
	v_and_b32_e32 v6, 0xffff0000, v20
	v_add_f32_e32 v3, v5, v3
	v_lshlrev_b32_e32 v5, 16, v20
	v_and_b32_e32 v12, 0xffff0000, v24
	v_mul_f32_e32 v6, v6, v6
	v_lshlrev_b32_e32 v7, 16, v24
	v_fmac_f32_e32 v6, v5, v5
	v_mul_f32_e32 v5, v12, v12
	v_fmac_f32_e32 v5, v7, v7
	v_and_b32_e32 v7, 0xffff0000, v21
	v_add_f32_e32 v5, v6, v5
	v_lshlrev_b32_e32 v6, 16, v21
	v_and_b32_e32 v13, 0xffff0000, v25
	v_mul_f32_e32 v7, v7, v7
	v_lshlrev_b32_e32 v12, 16, v25
	v_fmac_f32_e32 v7, v6, v6
	v_mul_f32_e32 v6, v13, v13
	v_fmac_f32_e32 v6, v12, v12
	v_add_f32_e32 v6, v7, v6
	v_and_b32_e32 v7, 0xffff0000, v22
	v_add_f32_e32 v5, v5, v6
	v_lshlrev_b32_e32 v6, 16, v22
	v_and_b32_e32 v13, 0xffff0000, v26
	v_mul_f32_e32 v7, v7, v7
	v_lshlrev_b32_e32 v12, 16, v26
	v_fmac_f32_e32 v7, v6, v6
	v_mul_f32_e32 v6, v13, v13
	v_fmac_f32_e32 v6, v12, v12
	v_add_f32_e32 v6, v7, v6
	v_and_b32_e32 v7, 0xffff0000, v23
	v_add_f32_e32 v5, v6, v5
	v_lshlrev_b32_e32 v6, 16, v23
	v_and_b32_e32 v13, 0xffff0000, v27
	v_mul_f32_e32 v7, v7, v7
	v_lshlrev_b32_e32 v12, 16, v27
	v_fmac_f32_e32 v7, v6, v6
	v_mul_f32_e32 v6, v13, v13
	v_fmac_f32_e32 v6, v12, v12
	v_add_f32_e32 v6, v7, v6
	v_lshlrev_b32_e32 v7, 16, v8
	v_and_b32_e32 v8, 0xffff0000, v8
	v_and_b32_e32 v13, 0xffff0000, v28
	v_mul_f32_e32 v8, v8, v8
	v_lshlrev_b32_e32 v12, 16, v28
	v_fmac_f32_e32 v8, v7, v7
	v_mul_f32_e32 v7, v13, v13
	v_fmac_f32_e32 v7, v12, v12
	v_add_f32_e32 v7, v8, v7
	v_lshlrev_b32_e32 v8, 16, v9
	v_and_b32_e32 v9, 0xffff0000, v9
	v_and_b32_e32 v13, 0xffff0000, v29
	v_mul_f32_e32 v9, v9, v9
	v_lshlrev_b32_e32 v12, 16, v29
	v_fmac_f32_e32 v9, v8, v8
	v_mul_f32_e32 v8, v13, v13
	v_fmac_f32_e32 v8, v12, v12
	v_add_f32_e32 v8, v9, v8
	v_and_b32_e32 v9, 0xffff0000, v10
	v_add_f32_e32 v7, v7, v8
	v_lshlrev_b32_e32 v8, 16, v10
	v_and_b32_e32 v12, 0xffff0000, v30
	v_mul_f32_e32 v9, v9, v9
	v_lshlrev_b32_e32 v10, 16, v30
	v_fmac_f32_e32 v9, v8, v8
	v_mul_f32_e32 v8, v12, v12
	v_fmac_f32_e32 v8, v10, v10
	v_add_f32_e32 v8, v9, v8
	v_and_b32_e32 v9, 0xffff0000, v11
	v_add_f32_e32 v7, v8, v7
	v_lshlrev_b32_e32 v8, 16, v11
	v_and_b32_e32 v11, 0xffff0000, v31
	v_mul_f32_e32 v9, v9, v9
	v_lshlrev_b32_e32 v10, 16, v31
	v_fmac_f32_e32 v9, v8, v8
	v_mul_f32_e32 v8, v11, v11
	v_fmac_f32_e32 v8, v10, v10
	v_add_f32_e32 v8, v9, v8
	v_add_f32_e32 v2, v3, v2
	v_add_f32_e32 v5, v6, v5
	v_add_f32_e32 v7, v8, v7
	v_mov_b32_e32 v4, v1
	v_mov_b32_e32 v3, v2
	v_mov_b32_e32 v6, v5
	v_mov_b32_e32 v8, v7
	v_permlane16_swap_b32_e32 v1, v4
	v_permlane16_swap_b32_e32 v2, v3
	v_permlane16_swap_b32_e32 v5, v6
	v_permlane16_swap_b32_e32 v7, v8
	v_add_f32_e32 v1, v1, v4
	v_add_f32_e32 v2, v2, v3
	v_add_f32_e32 v5, v5, v6
	v_add_f32_e32 v7, v7, v8
	v_mov_b32_e32 v4, v1
	v_mov_b32_e32 v3, v2
	v_mov_b32_e32 v6, v5
	v_mov_b32_e32 v8, v7
	v_sub_u32_e64 v9, s5, 4 clamp
	v_permlane32_swap_b32_e32 v1, v4
	v_permlane32_swap_b32_e32 v2, v3
	v_permlane32_swap_b32_e32 v5, v6
	v_permlane32_swap_b32_e32 v7, v8
	v_readfirstlane_b32 s77, v9
	s_cbranch_scc0 .LBB0_458
	s_min_i32 s0, s80, 0
	s_sub_i32 s0, s0, s76
	s_lshl_b32 s0, s0, 5
	s_add_i32 s6, s0, 0x1000
	s_cbranch_execnz .LBB0_460
	s_branch .LBB0_459
